# phase 3: V^T built by a workgroup-level LDS transpose (32 consecutive rows per step, 32-byte contiguous stores) instead of 16 scattered 2-byte stores per lane; on top of v10b
# speedup vs baseline: 1.0087x; 1.0037x over previous
; template <int PH>
; __device__ __forceinline__ void run_phase(const Args& args, LAS unsigned char* lds) {
;     ...
;                 const float* qg = args.in[14]; const float* kg = args.in[15];
;                 const int l16 = lane & 15, gq = lane >> 4;
;                 const float QS = 0.08838834764831845f * LOG2E;
;                 const f32x4 qga = *(const f32x4*)(qg + 8 * l16), qgb = *(const f32x4*)(qg + 8 * l16 + 4), kga = *(const f32x4*)(kg + 8 * l16), kgb = *(const f32x4*)(kg + 8 * l16 + 4);
;                 const float qgv[8] = {qga.x, qga.y, qga.z, qga.w, qgb.x, qgb.y, qgb.z, qgb.w}, kgv[8] = {kga.x, kga.y, kga.z, kga.w, kgb.x, kgb.y, kgb.z, kgb.w};
;                 const bool first = (l16 & 4) == 0;
;                 for (int grp = gw; grp < MT / 4; grp += NGW) {
;                     const int row = grp * 4 + gq;
;                     const bool lat = row < ML; const int b = lat ? (row >> 11) : ((row - ML) >> 8); const int t = lat ? (row & 2047) : ((row - ML) & 255);
;                     const int Tpos = lat ? CTXL + t : t;
;                     float cs[8], sn[8];
; #pragma unroll
;                     for (int k = 0; k < 8; ++k) { cs[k] = 1.f; sn[k] = 0.f; }
;                     if (lat) { const int pos = l16 < 8 ? (t >> 6) : (t & 63); const f32x4* tp = (const f32x4*)((const float*)(ws + OFF_ROPE32) + (pos * 32 + 8 * (l16 & 3)) * 2);
; #pragma unroll
;                         for (int k2 = 0; k2 < 4; ++k2) { const f32x4 tv = tp[k2]; cs[2 * k2] = tv.x; sn[2 * k2] = tv.y; cs[2 * k2 + 1] = tv.z; sn[2 * k2 + 1] = tv.w; } }
;                     const bf16_t* zr = Zb + (size_t)row * INE + 2048 + 8 * l16;
;                     u32x4 raw[12];
; #pragma unroll
;                     for (int h = 0; h < 12; ++h) raw[h] = *(const u32x4*)(zr + h * 128);
; #pragma unroll
;                     for (int h = 0; h < 10; ++h) {
;                         float x[8] = {bflo(raw[h].x), bfhi(raw[h].x), bflo(raw[h].y), bfhi(raw[h].y), bflo(raw[h].z), bfhi(raw[h].z), bflo(raw[h].w), bfhi(raw[h].w)};
;                         float ss = 0.f;
; #pragma unroll
;                         for (int k = 0; k < 8; ++k) ss += x[k] * x[k];
;                         ss += __shfl_xor(ss, 1); ss += __shfl_xor(ss, 2); ss += __shfl_xor(ss, 4); ss += __shfl_xor(ss, 8);
;                         const float rs = 1.0f / sqrtf(ss * (1.0f / 128.0f) + NEPS);
.LBB0_290:
	s_cmp_lt_i32 s86, 4
	s_cselect_b64 s[0:1], -1, 0
	s_cmp_gt_i32 s87, 3
	s_cselect_b64 s[2:3], -1, 0
	s_and_b64 s[0:1], s[0:1], s[2:3]
	s_andn2_b64 vcc, exec, s[0:1]
	s_cbranch_vccnz .LBB0_509
	v_lshrrev_b32_e32 v1, 4, v184
	v_and_b32_e32 v2, 15, v184
	v_mul_u32_u24_e32 v3, 0x1c00, v1
	v_lshl_add_u32 v3, v2, 5, v3
	v_lshlrev_b32_e32 v4, 10, v2
	v_lshl_add_u32 v4, v1, 1, v4
	v_lshlrev_b32_e32 v5, 5, v184
	v_lshrrev_b32_e32 v6, 1, v184
	v_and_b32_e32 v7, 1, v184
	v_mul_u32_u24_e32 v6, 0x1200, v6
	v_lshl_add_u32 v6, v7, 5, v6
	s_mov_b32 s0, s33
.Lvt_loop:
	s_cmp_ge_u32 s0, 0x240
	s_cbranch_scc1 .Lvt_done
	s_lshl_b32 s1, s0, 5
	s_mul_i32 s2, s1, 0x1c00
	s_add_u32 s4, s84, s2
	s_addc_u32 s5, s85, 0
	s_add_u32 s4, s4, 0x19001a00
	s_addc_u32 s5, s5, 0
	global_load_dwordx4 v[8:11], v3, s[4:5]
	global_load_dwordx4 v[12:15], v3, s[4:5] offset:16
	s_cmp_lt_u32 s1, 0x4000
	s_cbranch_scc0 .Lvt_ctx
	s_lshr_b32 s6, s1, 11
	s_and_b32 s7, s1, 0x7ff
	s_add_i32 s7, s7, 0x100
	s_branch .Lvt_addr
.Lvt_ctx:
	s_sub_i32 s8, s1, 0x4000
	s_lshr_b32 s6, s8, 8
	s_and_b32 s7, s8, 0xff
.Lvt_addr:
	s_mul_i32 s6, s6, 0x120000
	s_lshl_b32 s7, s7, 1
	s_add_i32 s6, s6, s7
	s_add_u32 s8, s84, s6
	s_addc_u32 s9, s85, 0
	s_add_u32 s8, s8, 0x2c000000
	s_addc_u32 s9, s9, 0
	s_waitcnt vmcnt(0)
	ds_write_b16 v4, v8 offset:0
	ds_write_b16_d16_hi v4, v8 offset:64
	ds_write_b16 v4, v9 offset:128
	ds_write_b16_d16_hi v4, v9 offset:192
	ds_write_b16 v4, v10 offset:256
	ds_write_b16_d16_hi v4, v10 offset:320
	ds_write_b16 v4, v11 offset:384
	ds_write_b16_d16_hi v4, v11 offset:448
	ds_write_b16 v4, v12 offset:512
	ds_write_b16_d16_hi v4, v12 offset:576
	ds_write_b16 v4, v13 offset:640
	ds_write_b16_d16_hi v4, v13 offset:704
	ds_write_b16 v4, v14 offset:768
	ds_write_b16_d16_hi v4, v14 offset:832
	ds_write_b16 v4, v15 offset:896
	ds_write_b16_d16_hi v4, v15 offset:960
	s_waitcnt lgkmcnt(0)
	s_barrier
	ds_read_b128 v[8:11], v5
	ds_read_b128 v[12:15], v5 offset:16
	s_waitcnt lgkmcnt(0)
	global_store_dwordx4 v6, v[8:11], s[8:9]
	global_store_dwordx4 v6, v[12:15], s[8:9] offset:16
	s_barrier
	s_add_i32 s0, s0, s88
	s_branch .Lvt_loop
.Lvt_done:
	v_readfirstlane_b32 s23, v184
	s_lshr_b32 s0, s23, 6
	s_lshl_b32 s1, s33, 3
	s_add_i32 s24, s0, s1
	s_add_u32 s6, s84, 0x19000000
	s_addc_u32 s7, s85, 0
	s_cmpk_gt_i32 s24, 0x11ff
	v_and_b32_e32 v67, 63, v184
	s_cbranch_scc1 .LBB0_296
	v_readlane_b32 s44, v254, 2
	v_readlane_b32 s45, v254, 3
	v_readlane_b32 s46, v254, 4
	v_readlane_b32 s47, v254, 5
	v_readlane_b32 s48, v254, 6
	v_readlane_b32 s49, v254, 7
	v_readlane_b32 s50, v254, 8
	v_readlane_b32 s51, v254, 9
	v_readlane_b32 s52, v254, 10
	v_readlane_b32 s53, v254, 11
	v_readlane_b32 s54, v254, 12
	v_readlane_b32 s55, v254, 13
	v_and_b32_e32 v18, 15, v184
	v_readlane_b32 s56, v254, 14
	v_readlane_b32 s57, v254, 15
	v_readlane_b32 s58, v254, 16
	v_readlane_b32 s59, v254, 17
	s_mov_b64 s[44:45], s[48:49]
	v_lshlrev_b32_e32 v12, 5, v18
	s_mov_b64 s[46:47], s[50:51]
	s_mov_b64 s[48:49], s[52:53]
	s_mov_b64 s[50:51], s[54:55]
	s_mov_b64 s[52:53], s[56:57]
	s_mov_b64 s[54:55], s[58:59]
	global_load_dwordx4 v[0:3], v12, s[54:55]
	global_load_dwordx4 v[4:7], v12, s[52:53]
	global_load_dwordx4 v[8:11], v12, s[54:55] offset:16
	s_nop 0
	global_load_dwordx4 v[12:15], v12, s[52:53] offset:16
	v_mov_b32_e32 v69, 0
	v_lshlrev_b32_e32 v68, 4, v18
	v_lshl_add_u64 v[16:17], s[84:85], 0, v[68:69]
	s_mov_b64 s[2:3], 0x25a00000
	v_lshl_add_u64 v[70:71], v[16:17], 0, s[2:3]
	v_mbcnt_lo_u32_b32 v17, -1, 0
	v_mbcnt_hi_u32_b32 v17, -1, v17
	v_and_b32_e32 v19, 64, v17
	v_lshlrev_b32_e32 v66, 3, v18
	v_cmp_gt_u32_e64 s[4:5], 8, v18
	v_xor_b32_e32 v18, 1, v17
	v_add_u32_e32 v19, 64, v19
	v_cmp_lt_i32_e32 vcc, v18, v19
	s_lshl_b32 s25, s88, 3
	s_add_u32 s8, s84, 0x2c000000
	v_cndmask_b32_e32 v18, v17, v18, vcc
	v_lshlrev_b32_e32 v82, 2, v18
	v_xor_b32_e32 v18, 2, v17
	v_cmp_lt_i32_e32 vcc, v18, v19
	s_addc_u32 s9, s85, 0
	v_and_b32_e32 v16, 4, v184
	v_cndmask_b32_e32 v18, v17, v18, vcc
	v_lshlrev_b32_e32 v83, 2, v18
	v_xor_b32_e32 v18, 4, v17
	v_cmp_lt_i32_e32 vcc, v18, v19
	v_cmp_eq_u32_e64 s[2:3], 0, v16
	s_add_u32 s10, s84, 0x2c4000
	v_cndmask_b32_e32 v18, v17, v18, vcc
	v_lshlrev_b32_e32 v84, 2, v18
	v_xor_b32_e32 v18, 8, v17
	v_lshlrev_b32_e32 v16, 4, v184
	v_cmp_lt_i32_e32 vcc, v18, v19
	s_addc_u32 s11, s85, 0
	v_and_b32_e32 v16, 48, v16
	v_cndmask_b32_e32 v17, v17, v18, vcc
	s_lshl_b32 s1, s33, 5
	s_lshl_b32 s0, s0, 2
	v_lshrrev_b32_e32 v75, 4, v67
	v_lshlrev_b32_e32 v85, 2, v17
	s_add_i32 s26, s1, s0
	s_lshl_b32 s27, s88, 5
	s_movk_i32 s28, 0x4000
	v_lshlrev_b32_e32 v86, 2, v16
	s_movk_i32 s29, 0x1c00
	s_mov_b64 s[14:15], 0x1000
	s_movk_i32 s30, 0x1000
	s_movk_i32 s31, 0x900
	v_mov_b32_e32 v87, 0x358637bd
	s_mov_b32 s34, 0xf800000
	v_mov_b32_e32 v88, 0x260
	s_mov_b32 s22, 0x3e0293ee
	s_mov_b32 s35, 0x28a00000
	s_movk_i32 s36, 0x1200
	s_movk_i32 s37, 0x2000
	s_movk_i32 s38, 0x3000
	s_movk_i32 s39, 0x5000
	s_movk_i32 s44, 0x6000
	s_movk_i32 s45, 0x7000
	s_branch .LBB0_294
; template <int PH>
; __device__ __forceinline__ void run_phase(const Args& args, LAS unsigned char* lds) {
;     ...
;                 for (int grp = gw; grp < MT / 4; grp += NGW) {
;                     const int row = grp * 4 + gq;
;                     const bool lat = row < ML; const int b = lat ? (row >> 11) : ((row - ML) >> 8); const int t = lat ? (row & 2047) : ((row - ML) & 255);
;                     const int Tpos = lat ? CTXL + t : t;
;                     float cs[8], sn[8];
; #pragma unroll
;                     for (int k = 0; k < 8; ++k) { cs[k] = 1.f; sn[k] = 0.f; }
;                     if (lat) { const int pos = l16 < 8 ? (t >> 6) : (t & 63); const f32x4* tp = (const f32x4*)((const float*)(ws + OFF_ROPE32) + (pos * 32 + 8 * (l16 & 3)) * 2);
; #pragma unroll
;                         for (int k2 = 0; k2 < 4; ++k2) { const f32x4 tv = tp[k2]; cs[2 * k2] = tv.x; sn[2 * k2] = tv.y; cs[2 * k2 + 1] = tv.z; sn[2 * k2 + 1] = tv.w; } }
;                     const bf16_t* zr = Zb + (size_t)row * INE + 2048 + 8 * l16;
;                     u32x4 raw[12];
; #pragma unroll
;                     for (int h = 0; h < 12; ++h) raw[h] = *(const u32x4*)(zr + h * 128);
; #pragma unroll
;                     for (int h = 0; h < 10; ++h) {
;                         float x[8] = {bflo(raw[h].x), bfhi(raw[h].x), bflo(raw[h].y), bfhi(raw[h].y), bflo(raw[h].z), bfhi(raw[h].z), bflo(raw[h].w), bfhi(raw[h].w)};
;                         float ss = 0.f;
; #pragma unroll
;                         for (int k = 0; k < 8; ++k) ss += x[k] * x[k];
;                         ss += __shfl_xor(ss, 1); ss += __shfl_xor(ss, 2); ss += __shfl_xor(ss, 4); ss += __shfl_xor(ss, 8);
;                         const float rs = 1.0f / sqrtf(ss * (1.0f / 128.0f) + NEPS);
;                         float o[8];
; #pragma unroll
;                         for (int k = 0; k < 8; ++k) { const float y = x[k] * rs * (h < 8 ? qgv[k] : kgv[k]); const float yo = __shfl_xor(y, 4);
;                             o[k] = first ? (y * cs[k] - yo * sn[k]) : (yo * sn[k] + y * cs[k]); if (h < 8) o[k] *= QS; }
.LBB0_293:
	s_or_b64 exec, exec, s[0:1]
	v_mov_b64_e32 v[30:31], s[6:7]
	v_mad_i64_i32 v[30:31], s[0:1], v32, s29, v[30:31]
	v_lshlrev_b32_e32 v68, 1, v66
	v_lshl_add_u64 v[30:31], v[30:31], 0, v[68:69]
	v_add_co_u32_e64 v34, s[0:1], s30, v30
	v_lshl_add_u64 v[80:81], v[30:31], 0, s[14:15]
	s_nop 0
	v_addc_co_u32_e64 v35, s[0:1], 0, v31, s[0:1]
	global_load_dwordx4 v[50:53], v[34:35], off
	global_load_dwordx4 v[46:49], v[80:81], off offset:256
	s_add_i32 s0, s26, 0xffffc000
	v_add_u32_e32 v30, 0x100, v33
	s_ashr_i32 s1, s24, 9
	v_and_b32_e32 v31, 0xff, v32
	v_ashrrev_i32_e32 v33, 31, v32
	s_lshr_b32 s0, s0, 8
	v_mov_b32_e32 v34, s1
	v_cndmask_b32_e32 v74, v31, v30, vcc
	v_lshlrev_b64 v[30:31], 11, v[32:33]
	v_mov_b32_e32 v32, s0
	v_lshl_add_u64 v[76:77], v[70:71], 0, v[30:31]
	v_cndmask_b32_e32 v89, v32, v34, vcc
	global_load_dwordx4 v[38:41], v[80:81], off offset:512
	global_load_dwordx4 v[62:65], v[80:81], off offset:768
	s_waitcnt lgkmcnt(0)
	global_load_dwordx4 v[54:57], v[80:81], off offset:1024
	global_load_dwordx4 v[42:45], v[80:81], off offset:1280
	global_load_dwordx4 v[34:37], v[80:81], off offset:1536
	global_load_dwordx4 v[30:33], v[80:81], off offset:2816
	s_add_i32 s24, s24, s25
	s_add_i32 s26, s26, s27
	s_cmpk_gt_i32 s24, 0x11ff
	s_waitcnt vmcnt(0)
	v_lshlrev_b32_e32 v94, 16, v50
	v_and_b32_e32 v95, 0xffff0000, v50
	v_lshlrev_b32_e32 v90, 16, v53
	v_and_b32_e32 v91, 0xffff0000, v53
	v_lshlrev_b32_e32 v92, 16, v52
	v_and_b32_e32 v93, 0xffff0000, v52
	v_lshlrev_b32_e32 v52, 16, v51
	v_and_b32_e32 v53, 0xffff0000, v51
	v_mul_f32_e32 v58, v94, v94
	v_mul_f32_e32 v59, v95, v95
	v_mul_f32_e32 v50, v52, v52
	v_mul_f32_e32 v51, v53, v53
	v_add_f32_e32 v58, v58, v59
	v_add_f32_e32 v50, v50, v58
	v_lshlrev_b32_e32 v96, 16, v49
	v_and_b32_e32 v97, 0xffff0000, v49
	v_lshlrev_b32_e32 v98, 16, v48
	v_and_b32_e32 v99, 0xffff0000, v48
	v_mul_f32_e32 v48, v92, v92
	v_mul_f32_e32 v49, v93, v93
	v_add_f32_e32 v50, v51, v50
	v_add_f32_e32 v48, v48, v50
	v_lshlrev_b32_e32 v100, 16, v47
	v_and_b32_e32 v101, 0xffff0000, v47
	v_lshlrev_b32_e32 v102, 16, v46
	v_and_b32_e32 v103, 0xffff0000, v46
	v_mul_f32_e32 v46, v90, v90
	v_mul_f32_e32 v47, v91, v91
	v_add_f32_e32 v48, v49, v48
	v_add_f32_e32 v46, v46, v48
	v_mul_f32_e32 v106, v102, v102
	v_mul_f32_e32 v107, v103, v103
	v_add_f32_e32 v46, v47, v46
	v_mul_f32_e32 v104, v100, v100
	v_mul_f32_e32 v105, v101, v101
	v_add_f32_e32 v59, v106, v107
	ds_bpermute_b32 v47, v82, v46
	v_add_f32_e32 v58, v104, v59
	v_mul_f32_e32 v78, v98, v98
	v_mul_f32_e32 v79, v99, v99
	v_add_f32_e32 v51, v105, v58
	v_add_f32_e32 v50, v78, v51
	v_mul_f32_e32 v60, v96, v96
	v_mul_f32_e32 v61, v97, v97
	v_add_f32_e32 v48, v79, v50
	v_add_f32_e32 v48, v60, v48
	s_waitcnt lgkmcnt(0)
	v_add_f32_e32 v78, v46, v47
	v_add_f32_e32 v50, v61, v48
	ds_bpermute_b32 v79, v83, v78
	ds_bpermute_b32 v51, v82, v50
	global_load_dwordx4 v[58:61], v[80:81], off offset:1792
	global_load_dwordx4 v[46:49], v[80:81], off offset:2048
	s_waitcnt lgkmcnt(1)
	v_add_f32_e32 v78, v78, v79
	s_waitcnt lgkmcnt(0)
	v_add_f32_e32 v104, v50, v51
	ds_bpermute_b32 v79, v84, v78
	ds_bpermute_b32 v105, v83, v104
	v_mad_u64_u32 v[50:51], s[0:1], v89, s31, v[74:75]
	v_ashrrev_i32_e32 v51, 31, v50
	s_waitcnt lgkmcnt(1)
	v_add_f32_e32 v78, v78, v79
	s_waitcnt lgkmcnt(0)
	v_add_f32_e32 v104, v104, v105
	ds_bpermute_b32 v79, v85, v78
	ds_bpermute_b32 v105, v84, v104
	v_lshlrev_b64 v[50:51], 9, v[50:51]
	s_waitcnt lgkmcnt(1)
	v_add_f32_e32 v78, v78, v79
	s_waitcnt lgkmcnt(0)
	v_add_f32_e32 v104, v104, v105
	v_fmamk_f32 v78, v78, 0x3c000000, v87
	ds_bpermute_b32 v105, v85, v104
	v_mul_f32_e32 v79, 0x4f800000, v78
	v_cmp_gt_f32_e32 vcc, s34, v78
	s_nop 1
	v_cndmask_b32_e32 v106, v78, v79, vcc
	v_sqrt_f32_e32 v107, v106
	v_lshl_add_u64 v[78:79], s[84:85], 0, v[50:51]
	s_waitcnt lgkmcnt(0)
	v_add_f32_e32 v50, v104, v105
	v_fmamk_f32 v110, v50, 0x3c000000, v87
	v_add_u32_e32 v50, -1, v107
	v_add_u32_e32 v51, 1, v107
	v_fma_f32 v104, -v50, v107, v106
	v_fma_f32 v105, -v51, v107, v106
	v_cmp_ge_f32_e64 s[0:1], 0, v104
	v_mul_f32_e32 v111, 0x4f800000, v110
	s_nop 0
	v_cndmask_b32_e64 v50, v107, v50, s[0:1]
	v_cmp_lt_f32_e64 s[0:1], 0, v105
	s_nop 1
	v_cndmask_b32_e64 v50, v50, v51, s[0:1]
	v_mul_f32_e32 v51, 0x37800000, v50
	v_cndmask_b32_e32 v50, v50, v51, vcc
	v_cmp_class_f32_e32 vcc, v106, v88
	s_nop 1
	v_cndmask_b32_e32 v50, v50, v106, vcc
	v_div_scale_f32 v51, s[0:1], v50, v50, 1.0
	v_rcp_f32_e32 v104, v51
	v_div_scale_f32 v105, vcc, 1.0, v50, 1.0
	v_fma_f32 v106, -v51, v104, 1.0
	v_fmac_f32_e32 v104, v106, v104
	v_mul_f32_e32 v106, v105, v104
	v_fma_f32 v107, -v51, v106, v105
	v_fmac_f32_e32 v106, v107, v104
	v_fma_f32 v51, -v51, v106, v105
	v_div_fmas_f32 v51, v51, v104, v106
	v_div_fixup_f32 v50, v51, v50, 1.0
	v_pk_mul_f32 v[52:53], v[50:51], v[52:53] op_sel_hi:[0,1]
	v_mul_f32_e32 v52, v6, v52
	v_mul_f32_e32 v53, v7, v53
	ds_bpermute_b32 v104, v84, v52
	ds_bpermute_b32 v105, v84, v53
	v_pk_mul_f32 v[92:93], v[50:51], v[92:93] op_sel_hi:[0,1]
	v_mul_f32_e32 v92, v12, v92
	v_mul_f32_e32 v93, v13, v93
	ds_bpermute_b32 v106, v84, v92
	ds_bpermute_b32 v107, v84, v93
	s_waitcnt lgkmcnt(2)
	v_mul_f32_e32 v104, v22, v104
	v_mul_f32_e32 v105, v23, v105
	v_cmp_gt_f32_e32 vcc, s34, v110
	v_cndmask_b32_e64 v105, v105, -v105, s[2:3]
	v_cndmask_b32_e64 v104, v104, -v104, s[2:3]
	v_fma_f32 v52, v24, v52, v104
	v_fma_f32 v53, v25, v53, v105
	v_cndmask_b32_e32 v104, v110, v111, vcc
	v_sqrt_f32_e32 v105, v104
	s_waitcnt lgkmcnt(0)
; __device__ __forceinline__ unsigned cvtpk(float lo, float hi) { const f32x2 v = {lo, hi}; const hbf16x2_t b = __builtin_convertvector(v, hbf16x2_t); return __builtin_bit_cast(unsigned, b); }
; template <int PH>
; __device__ __forceinline__ void run_phase(const Args& args, LAS unsigned char* lds) {
;     ...
;                     for (int h = 0; h < 10; ++h) {
;                         float x[8] = {bflo(raw[h].x), bfhi(raw[h].x), bflo(raw[h].y), bfhi(raw[h].y), bflo(raw[h].z), bfhi(raw[h].z), bflo(raw[h].w), bfhi(raw[h].w)};
;                         float ss = 0.f;
; #pragma unroll
;                         for (int k = 0; k < 8; ++k) ss += x[k] * x[k];
;                         ss += __shfl_xor(ss, 1); ss += __shfl_xor(ss, 2); ss += __shfl_xor(ss, 4); ss += __shfl_xor(ss, 8);
;                         const float rs = 1.0f / sqrtf(ss * (1.0f / 128.0f) + NEPS);
;                         float o[8];
; #pragma unroll
;                         for (int k = 0; k < 8; ++k) { const float y = x[k] * rs * (h < 8 ? qgv[k] : kgv[k]); const float yo = __shfl_xor(y, 4);
;                             o[k] = first ? (y * cs[k] - yo * sn[k]) : (yo * sn[k] + y * cs[k]); if (h < 8) o[k] *= QS; }
;                         u32x4 w; w.x = cvtpk(o[0], o[1]); w.y = cvtpk(o[2], o[3]); w.z = cvtpk(o[4], o[5]); w.w = cvtpk(o[6], o[7]);
;                         if (h < 8) *(u32x4*)(Qb + (size_t)row * 1024 + h * 128 + 8 * l16) = w;
;                         else *(u32x4*)(Kb + (size_t)(b * TK + Tpos) * 256 + (h - 8) * 128 + 8 * l16) = w;
	v_mul_f32_e32 v106, v16, v106
	v_mul_f32_e32 v107, v17, v107
	v_pk_mul_f32 v[94:95], v[50:51], v[94:95] op_sel_hi:[0,1]
	v_cndmask_b32_e64 v107, v107, -v107, s[2:3]
	v_cndmask_b32_e64 v106, v106, -v106, s[2:3]
	v_fma_f32 v92, v20, v92, v106
	v_fma_f32 v93, v21, v93, v107
	v_add_u32_e32 v106, -1, v105
	v_fma_f32 v107, -v106, v105, v104
	v_cmp_ge_f32_e64 s[0:1], 0, v107
	v_add_u32_e32 v107, 1, v105
	v_pk_mul_f32 v[50:51], v[50:51], v[90:91] op_sel_hi:[0,1]
	v_mul_f32_e32 v90, v4, v94
	v_mul_f32_e32 v91, v5, v95
	v_cndmask_b32_e64 v106, v105, v106, s[0:1]
	v_fma_f32 v105, -v107, v105, v104
	ds_bpermute_b32 v94, v84, v90
	ds_bpermute_b32 v95, v84, v91
	v_cmp_lt_f32_e64 s[0:1], 0, v105
	v_mul_f32_e32 v50, v14, v50
	v_mul_f32_e32 v51, v15, v51
	ds_bpermute_b32 v108, v84, v50
	v_cndmask_b32_e64 v105, v106, v107, s[0:1]
	ds_bpermute_b32 v109, v84, v51
	v_mul_f32_e32 v106, 0x37800000, v105
	v_cndmask_b32_e32 v105, v105, v106, vcc
	v_cmp_class_f32_e32 vcc, v104, v88
	s_waitcnt lgkmcnt(2)
	v_mul_f32_e32 v94, v26, v94
	v_mul_f32_e32 v95, v27, v95
	v_pk_mul_f32 v[52:53], v[52:53], s[22:23] op_sel_hi:[1,0]
	v_cndmask_b32_e32 v104, v105, v104, vcc
	v_div_scale_f32 v105, s[0:1], v104, v104, 1.0
	v_cndmask_b32_e64 v95, v95, -v95, s[2:3]
	v_cndmask_b32_e64 v94, v94, -v94, s[2:3]
	v_rcp_f32_e32 v106, v105
	v_fma_f32 v90, v28, v90, v94
	v_fma_f32 v91, v29, v91, v95
	s_waitcnt lgkmcnt(0)
	v_mul_f32_e32 v94, v18, v108
	v_mul_f32_e32 v95, v19, v109
	v_pk_mul_f32 v[90:91], v[90:91], s[22:23] op_sel_hi:[1,0]
	v_cndmask_b32_e64 v95, v95, -v95, s[2:3]
	v_cndmask_b32_e64 v94, v94, -v94, s[2:3]
	v_fma_f32 v50, v72, v50, v94
	v_fma_f32 v51, v73, v51, v95
	v_pk_mul_f32 v[92:93], v[92:93], s[22:23] op_sel_hi:[1,0]
	v_pk_mul_f32 v[94:95], v[50:51], s[22:23] op_sel_hi:[1,0]
	v_fma_f32 v51, -v105, v106, 1.0
	v_fmac_f32_e32 v106, v51, v106
	v_div_scale_f32 v51, vcc, 1.0, v104, 1.0
	v_cvt_pk_bf16_f32 v50, v90, v91
	v_mul_f32_e32 v90, v51, v106
	v_fma_f32 v91, -v105, v90, v51
	v_fmac_f32_e32 v90, v91, v106
	v_fma_f32 v51, -v105, v90, v51
	v_div_fmas_f32 v51, v51, v106, v90
	v_div_fixup_f32 v90, v51, v104, 1.0
	v_pk_mul_f32 v[102:103], v[90:91], v[102:103] op_sel_hi:[0,1]
	v_mul_f32_e32 v102, v4, v102
	v_mul_f32_e32 v103, v5, v103
	ds_bpermute_b32 v104, v84, v102
	ds_bpermute_b32 v105, v84, v103
	v_cvt_pk_bf16_f32 v51, v52, v53
	v_cvt_pk_bf16_f32 v52, v92, v93
	v_cvt_pk_bf16_f32 v53, v94, v95
	v_lshlrev_b32_e32 v108, 16, v38
	v_and_b32_e32 v109, 0xffff0000, v38
	global_store_dwordx4 v[76:77], v[50:53], off
	v_pk_mul_f32 v[94:95], v[90:91], v[98:99] op_sel_hi:[0,1]
	v_lshlrev_b32_e32 v98, 16, v41
	s_waitcnt lgkmcnt(0)
	v_mul_f32_e32 v50, v26, v104
	v_mul_f32_e32 v51, v27, v105
	v_lshlrev_b32_e32 v104, 16, v39
	v_and_b32_e32 v105, 0xffff0000, v39
	v_mul_f32_e32 v38, v108, v108
	v_mul_f32_e32 v39, v109, v109
	v_cndmask_b32_e64 v51, v51, -v51, s[2:3]
	v_cndmask_b32_e64 v50, v50, -v50, s[2:3]
	v_mul_f32_e32 v106, v104, v104
	v_mul_f32_e32 v107, v105, v105
	v_add_f32_e32 v38, v38, v39
	v_fma_f32 v50, v28, v102, v50
	v_fma_f32 v51, v29, v103, v51
	v_lshlrev_b32_e32 v102, 16, v40
	v_and_b32_e32 v103, 0xffff0000, v40
	v_add_f32_e32 v38, v106, v38
	v_and_b32_e32 v99, 0xffff0000, v41
	v_mul_f32_e32 v40, v102, v102
	v_mul_f32_e32 v41, v103, v103
	v_add_f32_e32 v38, v107, v38
	v_add_f32_e32 v38, v40, v38
	v_pk_mul_f32 v[52:53], v[90:91], v[100:101] op_sel_hi:[0,1]
	v_mul_f32_e32 v100, v98, v98
	v_mul_f32_e32 v101, v99, v99
	v_add_f32_e32 v38, v41, v38
	v_mul_f32_e32 v52, v6, v52
	v_mul_f32_e32 v53, v7, v53
	v_add_f32_e32 v38, v100, v38
	ds_bpermute_b32 v92, v84, v52
	ds_bpermute_b32 v93, v84, v53
	v_add_f32_e32 v91, v101, v38
	ds_bpermute_b32 v100, v82, v91
	v_mul_f32_e32 v38, v12, v94
	v_mul_f32_e32 v39, v13, v95
	ds_bpermute_b32 v40, v84, v38
	s_waitcnt lgkmcnt(2)
	v_mul_f32_e32 v92, v22, v92
	v_mul_f32_e32 v93, v23, v93
	ds_bpermute_b32 v41, v84, v39
	v_cndmask_b32_e64 v93, v93, -v93, s[2:3]
	v_cndmask_b32_e64 v92, v92, -v92, s[2:3]
	s_waitcnt lgkmcnt(2)
	v_add_f32_e32 v91, v91, v100
	v_fma_f32 v52, v24, v52, v92
	v_fma_f32 v53, v25, v53, v93
	ds_bpermute_b32 v92, v83, v91
	s_waitcnt lgkmcnt(1)
	v_mul_f32_e32 v40, v16, v40
	v_mul_f32_e32 v41, v17, v41
	v_pk_mul_f32 v[50:51], v[50:51], s[22:23] op_sel_hi:[1,0]
	v_cndmask_b32_e64 v41, v41, -v41, s[2:3]
	v_cndmask_b32_e64 v40, v40, -v40, s[2:3]
	s_waitcnt lgkmcnt(0)
	v_add_f32_e32 v94, v91, v92
	ds_bpermute_b32 v95, v84, v94
	v_pk_mul_f32 v[90:91], v[90:91], v[96:97] op_sel_hi:[0,1]
	v_mul_f32_e32 v90, v14, v90
	v_mul_f32_e32 v91, v15, v91
	ds_bpermute_b32 v92, v84, v90
	ds_bpermute_b32 v93, v84, v91
	s_waitcnt lgkmcnt(2)
	v_add_f32_e32 v94, v94, v95
	ds_bpermute_b32 v95, v85, v94
	v_fma_f32 v38, v20, v38, v40
	v_fma_f32 v39, v21, v39, v41
	v_lshlrev_b32_e32 v110, 16, v62
	s_waitcnt lgkmcnt(1)
	v_mul_f32_e32 v40, v18, v92
	v_mul_f32_e32 v41, v19, v93
	v_pk_mul_f32 v[38:39], v[38:39], s[22:23] op_sel_hi:[1,0]
	s_waitcnt lgkmcnt(0)
; __device__ __forceinline__ unsigned cvtpk(float lo, float hi) { const f32x2 v = {lo, hi}; const hbf16x2_t b = __builtin_convertvector(v, hbf16x2_t); return __builtin_bit_cast(unsigned, b); }
; template <int PH>
; __device__ __forceinline__ void run_phase(const Args& args, LAS unsigned char* lds) {
;     ...
;                     for (int h = 0; h < 10; ++h) {
;                         float x[8] = {bflo(raw[h].x), bfhi(raw[h].x), bflo(raw[h].y), bfhi(raw[h].y), bflo(raw[h].z), bfhi(raw[h].z), bflo(raw[h].w), bfhi(raw[h].w)};
;                         float ss = 0.f;
; #pragma unroll
;                         for (int k = 0; k < 8; ++k) ss += x[k] * x[k];
;                         ss += __shfl_xor(ss, 1); ss += __shfl_xor(ss, 2); ss += __shfl_xor(ss, 4); ss += __shfl_xor(ss, 8);
;                         const float rs = 1.0f / sqrtf(ss * (1.0f / 128.0f) + NEPS);
;                         float o[8];
; #pragma unroll
;                         for (int k = 0; k < 8; ++k) { const float y = x[k] * rs * (h < 8 ? qgv[k] : kgv[k]); const float yo = __shfl_xor(y, 4);
;                             o[k] = first ? (y * cs[k] - yo * sn[k]) : (yo * sn[k] + y * cs[k]); if (h < 8) o[k] *= QS; }
;                         u32x4 w; w.x = cvtpk(o[0], o[1]); w.y = cvtpk(o[2], o[3]); w.z = cvtpk(o[4], o[5]); w.w = cvtpk(o[6], o[7]);
;                         if (h < 8) *(u32x4*)(Qb + (size_t)row * 1024 + h * 128 + 8 * l16) = w;
;                         else *(u32x4*)(Kb + (size_t)(b * TK + Tpos) * 256 + (h - 8) * 128 + 8 * l16) = w;
	v_add_f32_e32 v92, v94, v95
	v_fmamk_f32 v92, v92, 0x3c000000, v87
	v_mul_f32_e32 v93, 0x4f800000, v92
	v_cmp_gt_f32_e32 vcc, s34, v92
	v_cndmask_b32_e64 v41, v41, -v41, s[2:3]
	v_cndmask_b32_e64 v40, v40, -v40, s[2:3]
	v_cndmask_b32_e32 v92, v92, v93, vcc
	v_sqrt_f32_e32 v93, v92
	v_fma_f32 v40, v72, v90, v40
	v_fma_f32 v41, v73, v91, v41
	v_and_b32_e32 v111, 0xffff0000, v62
	v_pk_mul_f32 v[52:53], v[52:53], s[22:23] op_sel_hi:[1,0]
	v_add_u32_e32 v90, -1, v93
	v_fma_f32 v91, -v90, v93, v92
	v_cmp_ge_f32_e64 s[0:1], 0, v91
	v_add_u32_e32 v91, 1, v93
	v_pk_mul_f32 v[40:41], v[40:41], s[22:23] op_sel_hi:[1,0]
	v_cndmask_b32_e64 v90, v93, v90, s[0:1]
	v_fma_f32 v93, -v91, v93, v92
	v_cmp_lt_f32_e64 s[0:1], 0, v93
	v_lshlrev_b32_e32 v106, 16, v63
	v_and_b32_e32 v107, 0xffff0000, v63
	v_cndmask_b32_e64 v90, v90, v91, s[0:1]
	v_mul_f32_e32 v91, 0x37800000, v90
	v_cndmask_b32_e32 v90, v90, v91, vcc
	v_cmp_class_f32_e32 vcc, v92, v88
	v_mul_f32_e32 v62, v110, v110
	v_mul_f32_e32 v63, v111, v111
	v_cvt_pk_bf16_f32 v91, v52, v53
	v_cndmask_b32_e32 v93, v90, v92, vcc
	v_div_scale_f32 v94, s[0:1], v93, v93, 1.0
	v_rcp_f32_e32 v95, v94
	v_cvt_pk_bf16_f32 v92, v38, v39
	v_cvt_pk_bf16_f32 v90, v50, v51
	v_add_f32_e32 v62, v62, v63
	v_fma_f32 v38, -v94, v95, 1.0
	v_fmac_f32_e32 v95, v38, v95
	v_div_scale_f32 v38, vcc, 1.0, v93, 1.0
	v_mul_f32_e32 v39, v38, v95
	v_fma_f32 v50, -v94, v39, v38
	v_fmac_f32_e32 v39, v50, v95
	v_fma_f32 v38, -v94, v39, v38
	v_div_fmas_f32 v38, v38, v95, v39
	v_div_fixup_f32 v94, v38, v93, 1.0
	v_pk_mul_f32 v[38:39], v[94:95], v[108:109] op_sel_hi:[0,1]
	v_mul_f32_e32 v96, v4, v38
	v_mul_f32_e32 v97, v5, v39
	ds_bpermute_b32 v100, v84, v96
	ds_bpermute_b32 v101, v84, v97
	v_cvt_pk_bf16_f32 v93, v40, v41
	global_load_dwordx4 v[50:53], v[80:81], off offset:2304
	global_load_dwordx4 v[38:41], v[80:81], off offset:2560
	v_mul_f32_e32 v108, v106, v106
	v_mul_f32_e32 v109, v107, v107
	global_store_dwordx4 v[76:77], v[90:93], off offset:256
	s_waitcnt lgkmcnt(0)
	v_mul_f32_e32 v80, v26, v100
	v_mul_f32_e32 v81, v27, v101
	v_add_f32_e32 v62, v108, v62
	v_pk_mul_f32 v[90:91], v[94:95], v[104:105] op_sel_hi:[0,1]
	v_cndmask_b32_e64 v81, v81, -v81, s[2:3]
	v_cndmask_b32_e64 v80, v80, -v80, s[2:3]
	v_lshlrev_b32_e32 v104, 16, v64
	v_and_b32_e32 v105, 0xffff0000, v64
	v_fma_f32 v80, v28, v96, v80
	v_fma_f32 v81, v29, v97, v81
	v_lshlrev_b32_e32 v96, 16, v65
	v_and_b32_e32 v97, 0xffff0000, v65
	v_mul_f32_e32 v64, v104, v104
	v_mul_f32_e32 v65, v105, v105
	v_add_f32_e32 v62, v109, v62
	v_add_f32_e32 v62, v64, v62
	v_mul_f32_e32 v100, v96, v96
	v_mul_f32_e32 v101, v97, v97
	v_add_f32_e32 v62, v65, v62
	v_add_f32_e32 v62, v100, v62
	v_add_f32_e32 v95, v101, v62
	ds_bpermute_b32 v100, v82, v95
	v_mul_f32_e32 v90, v6, v90
	v_mul_f32_e32 v91, v7, v91
	ds_bpermute_b32 v92, v84, v90
	ds_bpermute_b32 v93, v84, v91
	v_pk_mul_f32 v[62:63], v[94:95], v[102:103] op_sel_hi:[0,1]
	s_waitcnt lgkmcnt(2)
	v_add_f32_e32 v95, v95, v100
	ds_bpermute_b32 v100, v83, v95
	v_mul_f32_e32 v62, v12, v62
	v_mul_f32_e32 v63, v13, v63
	s_waitcnt lgkmcnt(1)
	v_mul_f32_e32 v92, v22, v92
	v_mul_f32_e32 v93, v23, v93
	ds_bpermute_b32 v64, v84, v62
	v_cndmask_b32_e64 v93, v93, -v93, s[2:3]
	v_cndmask_b32_e64 v92, v92, -v92, s[2:3]
	v_fma_f32 v90, v24, v90, v92
	v_fma_f32 v91, v25, v91, v93
	s_waitcnt lgkmcnt(1)
	v_add_f32_e32 v92, v95, v100
	ds_bpermute_b32 v93, v84, v92
	ds_bpermute_b32 v65, v84, v63
	v_pk_mul_f32 v[80:81], v[80:81], s[22:23] op_sel_hi:[1,0]
	v_pk_mul_f32 v[90:91], v[90:91], s[22:23] op_sel_hi:[1,0]
	v_and_b32_e32 v101, 0xffff0000, v55
	s_waitcnt lgkmcnt(1)
	v_add_f32_e32 v95, v92, v93
	ds_bpermute_b32 v100, v85, v95
	s_waitcnt lgkmcnt(1)
	v_mul_f32_e32 v64, v16, v64
	v_mul_f32_e32 v65, v17, v65
	v_cndmask_b32_e64 v65, v65, -v65, s[2:3]
	v_cndmask_b32_e64 v64, v64, -v64, s[2:3]
	v_fma_f32 v62, v20, v62, v64
	v_fma_f32 v63, v21, v63, v65
	v_pk_mul_f32 v[64:65], v[62:63], s[22:23] op_sel_hi:[1,0]
	v_pk_mul_f32 v[62:63], v[94:95], v[98:99] op_sel_hi:[0,1]
	s_waitcnt lgkmcnt(0)
	v_add_f32_e32 v94, v95, v100
	v_fmamk_f32 v94, v94, 0x3c000000, v87
	v_mul_f32_e32 v95, 0x4f800000, v94
	v_cmp_gt_f32_e32 vcc, s34, v94
	v_mul_f32_e32 v62, v14, v62
	v_mul_f32_e32 v63, v15, v63
	ds_bpermute_b32 v92, v84, v62
	v_cndmask_b32_e32 v94, v94, v95, vcc
	v_sqrt_f32_e32 v95, v94
	ds_bpermute_b32 v93, v84, v63
	v_cvt_pk_bf16_f32 v64, v64, v65
	v_lshlrev_b32_e32 v100, 16, v55
	v_add_u32_e32 v98, -1, v95
	v_fma_f32 v99, -v98, v95, v94
	v_cmp_ge_f32_e64 s[0:1], 0, v99
	v_add_u32_e32 v99, 1, v95
	s_waitcnt lgkmcnt(0)
	v_mul_f32_e32 v92, v18, v92
	v_mul_f32_e32 v93, v19, v93
	v_cndmask_b32_e64 v98, v95, v98, s[0:1]
	v_fma_f32 v95, -v99, v95, v94
	v_cmp_lt_f32_e64 s[0:1], 0, v95
	v_cndmask_b32_e64 v93, v93, -v93, s[2:3]
	v_cndmask_b32_e64 v92, v92, -v92, s[2:3]
	v_cndmask_b32_e64 v95, v98, v99, s[0:1]
	v_mul_f32_e32 v98, 0x37800000, v95
	v_cndmask_b32_e32 v95, v95, v98, vcc
	v_cmp_class_f32_e32 vcc, v94, v88
	v_fma_f32 v62, v72, v62, v92
	v_fma_f32 v63, v73, v63, v93
	v_mul_f32_e32 v102, v100, v100
	v_mul_f32_e32 v103, v101, v101
	v_cndmask_b32_e32 v94, v95, v94, vcc
	v_div_scale_f32 v95, s[0:1], v94, v94, 1.0
	v_rcp_f32_e32 v98, v95
	v_pk_mul_f32 v[92:93], v[62:63], s[22:23] op_sel_hi:[1,0]
	v_cvt_pk_bf16_f32 v62, v80, v81
	v_cvt_pk_bf16_f32 v65, v92, v93
	v_fma_f32 v63, -v95, v98, 1.0
	v_fmac_f32_e32 v98, v63, v98
	v_div_scale_f32 v63, vcc, 1.0, v94, 1.0
	v_mul_f32_e32 v80, v63, v98
	v_fma_f32 v81, -v95, v80, v63
	v_fmac_f32_e32 v80, v81, v98
	v_fma_f32 v63, -v95, v80, v63
	v_div_fmas_f32 v63, v63, v98, v80
	v_div_fixup_f32 v80, v63, v94, 1.0
	v_pk_mul_f32 v[94:95], v[80:81], v[110:111] op_sel_hi:[0,1]
	v_mul_f32_e32 v94, v4, v94
	v_mul_f32_e32 v95, v5, v95
	ds_bpermute_b32 v98, v84, v94
	ds_bpermute_b32 v99, v84, v95
	v_cvt_pk_bf16_f32 v63, v90, v91
	global_store_dwordx4 v[76:77], v[62:65], off offset:512
	v_lshlrev_b32_e32 v92, 16, v57
	v_and_b32_e32 v93, 0xffff0000, v57
	v_pk_mul_f32 v[64:65], v[80:81], v[106:107] op_sel_hi:[0,1]
	v_lshlrev_b32_e32 v106, 16, v54
	v_and_b32_e32 v107, 0xffff0000, v54
	v_mul_f32_e32 v54, v106, v106
	v_mul_f32_e32 v55, v107, v107
	s_waitcnt lgkmcnt(0)
; __device__ __forceinline__ unsigned cvtpk(float lo, float hi) { const f32x2 v = {lo, hi}; const hbf16x2_t b = __builtin_convertvector(v, hbf16x2_t); return __builtin_bit_cast(unsigned, b); }
; template <int PH>
; __device__ __forceinline__ void run_phase(const Args& args, LAS unsigned char* lds) {
;     ...
;                     for (int h = 0; h < 10; ++h) {
;                         float x[8] = {bflo(raw[h].x), bfhi(raw[h].x), bflo(raw[h].y), bfhi(raw[h].y), bflo(raw[h].z), bfhi(raw[h].z), bflo(raw[h].w), bfhi(raw[h].w)};
;                         float ss = 0.f;
; #pragma unroll
;                         for (int k = 0; k < 8; ++k) ss += x[k] * x[k];
;                         ss += __shfl_xor(ss, 1); ss += __shfl_xor(ss, 2); ss += __shfl_xor(ss, 4); ss += __shfl_xor(ss, 8);
;                         const float rs = 1.0f / sqrtf(ss * (1.0f / 128.0f) + NEPS);
;                         float o[8];
; #pragma unroll
;                         for (int k = 0; k < 8; ++k) { const float y = x[k] * rs * (h < 8 ? qgv[k] : kgv[k]); const float yo = __shfl_xor(y, 4);
;                             o[k] = first ? (y * cs[k] - yo * sn[k]) : (yo * sn[k] + y * cs[k]); if (h < 8) o[k] *= QS; }
;                         u32x4 w; w.x = cvtpk(o[0], o[1]); w.y = cvtpk(o[2], o[3]); w.z = cvtpk(o[4], o[5]); w.w = cvtpk(o[6], o[7]);
;                         if (h < 8) *(u32x4*)(Qb + (size_t)row * 1024 + h * 128 + 8 * l16) = w;
;                         else *(u32x4*)(Kb + (size_t)(b * TK + Tpos) * 256 + (h - 8) * 128 + 8 * l16) = w;
	v_mul_f32_e32 v62, v26, v98
	v_mul_f32_e32 v63, v27, v99
	v_add_f32_e32 v54, v54, v55
	v_lshlrev_b32_e32 v98, 16, v56
	v_and_b32_e32 v99, 0xffff0000, v56
	v_add_f32_e32 v54, v102, v54
	v_mul_f32_e32 v56, v98, v98
	v_mul_f32_e32 v57, v99, v99
	v_add_f32_e32 v54, v103, v54
	v_cndmask_b32_e64 v63, v63, -v63, s[2:3]
	v_cndmask_b32_e64 v62, v62, -v62, s[2:3]
	v_add_f32_e32 v54, v56, v54
	v_fma_f32 v62, v28, v94, v62
	v_fma_f32 v63, v29, v95, v63
	v_mul_f32_e32 v94, v92, v92
	v_mul_f32_e32 v95, v93, v93
	v_add_f32_e32 v54, v57, v54
	v_add_f32_e32 v54, v94, v54
	v_add_f32_e32 v81, v95, v54
	ds_bpermute_b32 v94, v82, v81
	v_mul_f32_e32 v64, v6, v64
	v_mul_f32_e32 v65, v7, v65
	ds_bpermute_b32 v90, v84, v64
	ds_bpermute_b32 v91, v84, v65
	v_pk_mul_f32 v[54:55], v[80:81], v[104:105] op_sel_hi:[0,1]
	s_waitcnt lgkmcnt(2)
	v_add_f32_e32 v81, v81, v94
	ds_bpermute_b32 v94, v83, v81
	v_mul_f32_e32 v54, v12, v54
	v_mul_f32_e32 v55, v13, v55
	s_waitcnt lgkmcnt(1)
	v_mul_f32_e32 v90, v22, v90
	v_mul_f32_e32 v91, v23, v91
	ds_bpermute_b32 v56, v84, v54
	v_cndmask_b32_e64 v91, v91, -v91, s[2:3]
	v_cndmask_b32_e64 v90, v90, -v90, s[2:3]
	s_waitcnt lgkmcnt(1)
	v_add_f32_e32 v81, v81, v94
	v_fma_f32 v64, v24, v64, v90
	v_fma_f32 v65, v25, v65, v91
	ds_bpermute_b32 v90, v84, v81
	ds_bpermute_b32 v57, v84, v55
	v_pk_mul_f32 v[62:63], v[62:63], s[22:23] op_sel_hi:[1,0]
	v_pk_mul_f32 v[64:65], v[64:65], s[22:23] op_sel_hi:[1,0]
	v_lshlrev_b32_e32 v102, 16, v42
	s_waitcnt lgkmcnt(1)
	v_add_f32_e32 v90, v81, v90
	ds_bpermute_b32 v91, v85, v90
	s_waitcnt lgkmcnt(1)
	v_mul_f32_e32 v56, v16, v56
	v_mul_f32_e32 v57, v17, v57
	v_and_b32_e32 v103, 0xffff0000, v42
	v_cndmask_b32_e64 v57, v57, -v57, s[2:3]
	v_cndmask_b32_e64 v56, v56, -v56, s[2:3]
	s_waitcnt lgkmcnt(0)
	v_add_f32_e32 v90, v90, v91
	v_fmamk_f32 v90, v90, 0x3c000000, v87
	v_mul_f32_e32 v91, 0x4f800000, v90
	v_cmp_gt_f32_e32 vcc, s34, v90
	v_fma_f32 v54, v20, v54, v56
	v_fma_f32 v55, v21, v55, v57
	v_cndmask_b32_e32 v90, v90, v91, vcc
	v_sqrt_f32_e32 v91, v90
	v_pk_mul_f32 v[56:57], v[54:55], s[22:23] op_sel_hi:[1,0]
	v_pk_mul_f32 v[54:55], v[80:81], v[96:97] op_sel_hi:[0,1]
	v_mul_f32_e32 v54, v14, v54
	v_mul_f32_e32 v55, v15, v55
	v_add_u32_e32 v94, -1, v91
	v_fma_f32 v95, -v94, v91, v90
	v_cmp_ge_f32_e64 s[0:1], 0, v95
	v_add_u32_e32 v95, 1, v91
	ds_bpermute_b32 v80, v84, v54
	v_cndmask_b32_e64 v94, v91, v94, s[0:1]
	v_fma_f32 v91, -v95, v91, v90
	v_cmp_lt_f32_e64 s[0:1], 0, v91
	ds_bpermute_b32 v81, v84, v55
	v_cvt_pk_bf16_f32 v56, v56, v57
	v_cndmask_b32_e64 v91, v94, v95, s[0:1]
	v_mul_f32_e32 v94, 0x37800000, v91
	v_cndmask_b32_e32 v91, v91, v94, vcc
	v_cmp_class_f32_e32 vcc, v90, v88
	s_waitcnt lgkmcnt(0)
	v_mul_f32_e32 v80, v18, v80
	v_mul_f32_e32 v81, v19, v81
	v_lshlrev_b32_e32 v96, 16, v43
	v_cndmask_b32_e32 v90, v91, v90, vcc
	v_div_scale_f32 v91, s[0:1], v90, v90, 1.0
	v_rcp_f32_e32 v94, v91
	v_cndmask_b32_e64 v81, v81, -v81, s[2:3]
	v_cndmask_b32_e64 v80, v80, -v80, s[2:3]
	v_fma_f32 v54, v72, v54, v80
	v_fma_f32 v55, v73, v55, v81
	v_and_b32_e32 v97, 0xffff0000, v43
	v_pk_mul_f32 v[80:81], v[54:55], s[22:23] op_sel_hi:[1,0]
	v_fma_f32 v55, -v91, v94, 1.0
	v_fmac_f32_e32 v94, v55, v94
	v_div_scale_f32 v55, vcc, 1.0, v90, 1.0
	v_cvt_pk_bf16_f32 v54, v62, v63
	v_mul_f32_e32 v62, v55, v94
	v_fma_f32 v63, -v91, v62, v55
	v_fmac_f32_e32 v62, v63, v94
	v_fma_f32 v55, -v91, v62, v55
	v_div_fmas_f32 v55, v55, v94, v62
	v_div_fixup_f32 v62, v55, v90, 1.0
	v_pk_mul_f32 v[90:91], v[62:63], v[106:107] op_sel_hi:[0,1]
	v_mul_f32_e32 v90, v4, v90
	v_mul_f32_e32 v91, v5, v91
	ds_bpermute_b32 v94, v84, v90
	ds_bpermute_b32 v95, v84, v91
	v_cvt_pk_bf16_f32 v55, v64, v65
	v_cvt_pk_bf16_f32 v57, v80, v81
	v_mul_f32_e32 v42, v102, v102
	v_mul_f32_e32 v43, v103, v103
	global_store_dwordx4 v[76:77], v[54:57], off offset:768
	v_add_f32_e32 v42, v42, v43
	v_lshlrev_b32_e32 v80, 16, v45
	v_pk_mul_f32 v[56:57], v[62:63], v[100:101] op_sel_hi:[0,1]
	v_mul_f32_e32 v100, v96, v96
	v_mul_f32_e32 v101, v97, v97
	s_waitcnt lgkmcnt(0)
	v_mul_f32_e32 v54, v26, v94
	v_mul_f32_e32 v55, v27, v95
	v_lshlrev_b32_e32 v94, 16, v44
	v_and_b32_e32 v95, 0xffff0000, v44
	v_add_f32_e32 v42, v100, v42
	v_and_b32_e32 v81, 0xffff0000, v45
	v_mul_f32_e32 v44, v94, v94
	v_mul_f32_e32 v45, v95, v95
	v_add_f32_e32 v42, v101, v42
	v_cndmask_b32_e64 v55, v55, -v55, s[2:3]
	v_cndmask_b32_e64 v54, v54, -v54, s[2:3]
	v_add_f32_e32 v42, v44, v42
	v_fma_f32 v54, v28, v90, v54
	v_fma_f32 v55, v29, v91, v55
	v_mul_f32_e32 v90, v80, v80
	v_mul_f32_e32 v91, v81, v81
	v_add_f32_e32 v42, v45, v42
	v_add_f32_e32 v42, v90, v42
	v_add_f32_e32 v63, v91, v42
	ds_bpermute_b32 v90, v82, v63
	v_mul_f32_e32 v56, v6, v56
	v_mul_f32_e32 v57, v7, v57
	ds_bpermute_b32 v64, v84, v56
	ds_bpermute_b32 v65, v84, v57
	v_pk_mul_f32 v[42:43], v[62:63], v[98:99] op_sel_hi:[0,1]
	s_waitcnt lgkmcnt(2)
	v_add_f32_e32 v63, v63, v90
	ds_bpermute_b32 v90, v83, v63
	v_mul_f32_e32 v42, v12, v42
	v_mul_f32_e32 v43, v13, v43
	s_waitcnt lgkmcnt(1)
	v_mul_f32_e32 v64, v22, v64
	v_mul_f32_e32 v65, v23, v65
	ds_bpermute_b32 v44, v84, v42
	v_cndmask_b32_e64 v65, v65, -v65, s[2:3]
	v_cndmask_b32_e64 v64, v64, -v64, s[2:3]
	s_waitcnt lgkmcnt(1)
	v_add_f32_e32 v63, v63, v90
	v_fma_f32 v56, v24, v56, v64
	v_fma_f32 v57, v25, v57, v65
	ds_bpermute_b32 v64, v84, v63
	ds_bpermute_b32 v45, v84, v43
	v_pk_mul_f32 v[54:55], v[54:55], s[22:23] op_sel_hi:[1,0]
	v_pk_mul_f32 v[56:57], v[56:57], s[22:23] op_sel_hi:[1,0]
	v_lshlrev_b32_e32 v98, 16, v34
	s_waitcnt lgkmcnt(1)
	v_add_f32_e32 v64, v63, v64
	ds_bpermute_b32 v65, v85, v64
	s_waitcnt lgkmcnt(1)
; __device__ __forceinline__ unsigned cvtpk(float lo, float hi) { const f32x2 v = {lo, hi}; const hbf16x2_t b = __builtin_convertvector(v, hbf16x2_t); return __builtin_bit_cast(unsigned, b); }
; template <int PH>
; __device__ __forceinline__ void run_phase(const Args& args, LAS unsigned char* lds) {
;     ...
;                     for (int h = 0; h < 10; ++h) {
;                         float x[8] = {bflo(raw[h].x), bfhi(raw[h].x), bflo(raw[h].y), bfhi(raw[h].y), bflo(raw[h].z), bfhi(raw[h].z), bflo(raw[h].w), bfhi(raw[h].w)};
;                         float ss = 0.f;
; #pragma unroll
;                         for (int k = 0; k < 8; ++k) ss += x[k] * x[k];
;                         ss += __shfl_xor(ss, 1); ss += __shfl_xor(ss, 2); ss += __shfl_xor(ss, 4); ss += __shfl_xor(ss, 8);
;                         const float rs = 1.0f / sqrtf(ss * (1.0f / 128.0f) + NEPS);
;                         float o[8];
; #pragma unroll
;                         for (int k = 0; k < 8; ++k) { const float y = x[k] * rs * (h < 8 ? qgv[k] : kgv[k]); const float yo = __shfl_xor(y, 4);
;                             o[k] = first ? (y * cs[k] - yo * sn[k]) : (yo * sn[k] + y * cs[k]); if (h < 8) o[k] *= QS; }
;                         u32x4 w; w.x = cvtpk(o[0], o[1]); w.y = cvtpk(o[2], o[3]); w.z = cvtpk(o[4], o[5]); w.w = cvtpk(o[6], o[7]);
;                         if (h < 8) *(u32x4*)(Qb + (size_t)row * 1024 + h * 128 + 8 * l16) = w;
;                         else *(u32x4*)(Kb + (size_t)(b * TK + Tpos) * 256 + (h - 8) * 128 + 8 * l16) = w;
	v_mul_f32_e32 v44, v16, v44
	v_mul_f32_e32 v45, v17, v45
	v_and_b32_e32 v99, 0xffff0000, v34
	v_cndmask_b32_e64 v45, v45, -v45, s[2:3]
	v_cndmask_b32_e64 v44, v44, -v44, s[2:3]
	s_waitcnt lgkmcnt(0)
	v_add_f32_e32 v64, v64, v65
	v_fmamk_f32 v64, v64, 0x3c000000, v87
	v_mul_f32_e32 v65, 0x4f800000, v64
	v_cmp_gt_f32_e32 vcc, s34, v64
	v_fma_f32 v42, v20, v42, v44
	v_fma_f32 v43, v21, v43, v45
	v_cndmask_b32_e32 v64, v64, v65, vcc
	v_sqrt_f32_e32 v65, v64
	v_pk_mul_f32 v[44:45], v[42:43], s[22:23] op_sel_hi:[1,0]
	v_pk_mul_f32 v[42:43], v[62:63], v[92:93] op_sel_hi:[0,1]
	v_mul_f32_e32 v42, v14, v42
	v_mul_f32_e32 v43, v15, v43
	v_add_u32_e32 v90, -1, v65
	v_fma_f32 v91, -v90, v65, v64
	v_cmp_ge_f32_e64 s[0:1], 0, v91
	v_add_u32_e32 v91, 1, v65
	ds_bpermute_b32 v62, v84, v42
	v_cndmask_b32_e64 v90, v65, v90, s[0:1]
	v_fma_f32 v65, -v91, v65, v64
	v_cmp_lt_f32_e64 s[0:1], 0, v65
	ds_bpermute_b32 v63, v84, v43
	v_cvt_pk_bf16_f32 v44, v44, v45
	v_cndmask_b32_e64 v65, v90, v91, s[0:1]
	v_mul_f32_e32 v90, 0x37800000, v65
	v_cndmask_b32_e32 v65, v65, v90, vcc
	v_cmp_class_f32_e32 vcc, v64, v88
	s_waitcnt lgkmcnt(0)
	v_mul_f32_e32 v62, v18, v62
	v_mul_f32_e32 v63, v19, v63
	v_lshlrev_b32_e32 v92, 16, v35
	v_cndmask_b32_e32 v64, v65, v64, vcc
	v_div_scale_f32 v65, s[0:1], v64, v64, 1.0
	v_rcp_f32_e32 v90, v65
	v_cndmask_b32_e64 v63, v63, -v63, s[2:3]
	v_cndmask_b32_e64 v62, v62, -v62, s[2:3]
	v_fma_f32 v42, v72, v42, v62
	v_fma_f32 v43, v73, v43, v63
	v_and_b32_e32 v93, 0xffff0000, v35
	v_pk_mul_f32 v[62:63], v[42:43], s[22:23] op_sel_hi:[1,0]
	v_fma_f32 v43, -v65, v90, 1.0
	v_fmac_f32_e32 v90, v43, v90
	v_div_scale_f32 v43, vcc, 1.0, v64, 1.0
	v_cvt_pk_bf16_f32 v42, v54, v55
	v_mul_f32_e32 v54, v43, v90
	v_fma_f32 v55, -v65, v54, v43
	v_fmac_f32_e32 v54, v55, v90
	v_fma_f32 v43, -v65, v54, v43
	v_div_fmas_f32 v43, v43, v90, v54
	v_div_fixup_f32 v54, v43, v64, 1.0
	v_pk_mul_f32 v[64:65], v[54:55], v[102:103] op_sel_hi:[0,1]
	v_mul_f32_e32 v64, v4, v64
	v_mul_f32_e32 v65, v5, v65
	ds_bpermute_b32 v90, v84, v64
	ds_bpermute_b32 v91, v84, v65
	v_cvt_pk_bf16_f32 v43, v56, v57
	v_cvt_pk_bf16_f32 v45, v62, v63
	v_mul_f32_e32 v34, v98, v98
	v_mul_f32_e32 v35, v99, v99
	global_store_dwordx4 v[76:77], v[42:45], off offset:1024
	v_add_f32_e32 v34, v34, v35
	v_lshlrev_b32_e32 v62, 16, v37
	v_pk_mul_f32 v[44:45], v[54:55], v[96:97] op_sel_hi:[0,1]
	v_mul_f32_e32 v96, v92, v92
	v_mul_f32_e32 v97, v93, v93
	s_waitcnt lgkmcnt(0)
	v_mul_f32_e32 v42, v26, v90
	v_mul_f32_e32 v43, v27, v91
	v_lshlrev_b32_e32 v90, 16, v36
	v_and_b32_e32 v91, 0xffff0000, v36
	v_add_f32_e32 v34, v96, v34
	v_and_b32_e32 v63, 0xffff0000, v37
	v_mul_f32_e32 v36, v90, v90
	v_mul_f32_e32 v37, v91, v91
	v_add_f32_e32 v34, v97, v34
	v_cndmask_b32_e64 v43, v43, -v43, s[2:3]
	v_cndmask_b32_e64 v42, v42, -v42, s[2:3]
	v_add_f32_e32 v34, v36, v34
	v_fma_f32 v42, v28, v64, v42
	v_fma_f32 v43, v29, v65, v43
	v_mul_f32_e32 v64, v62, v62
	v_mul_f32_e32 v65, v63, v63
	v_add_f32_e32 v34, v37, v34
	v_add_f32_e32 v34, v64, v34
	v_add_f32_e32 v55, v65, v34
	ds_bpermute_b32 v64, v82, v55
	v_mul_f32_e32 v44, v6, v44
	v_mul_f32_e32 v45, v7, v45
	ds_bpermute_b32 v56, v84, v44
	ds_bpermute_b32 v57, v84, v45
	v_pk_mul_f32 v[34:35], v[54:55], v[94:95] op_sel_hi:[0,1]
	s_waitcnt lgkmcnt(2)
	v_add_f32_e32 v55, v55, v64
	ds_bpermute_b32 v64, v83, v55
	v_mul_f32_e32 v34, v12, v34
	v_mul_f32_e32 v35, v13, v35
	s_waitcnt lgkmcnt(1)
	v_mul_f32_e32 v56, v22, v56
	v_mul_f32_e32 v57, v23, v57
	ds_bpermute_b32 v36, v84, v34
	v_cndmask_b32_e64 v57, v57, -v57, s[2:3]
	v_cndmask_b32_e64 v56, v56, -v56, s[2:3]
	s_waitcnt lgkmcnt(1)
	v_add_f32_e32 v55, v55, v64
	v_fma_f32 v44, v24, v44, v56
	v_fma_f32 v45, v25, v45, v57
	ds_bpermute_b32 v56, v84, v55
	ds_bpermute_b32 v37, v84, v35
	v_pk_mul_f32 v[42:43], v[42:43], s[22:23] op_sel_hi:[1,0]
	v_pk_mul_f32 v[44:45], v[44:45], s[22:23] op_sel_hi:[1,0]
	s_waitcnt vmcnt(8)
	v_lshlrev_b32_e32 v94, 16, v58
	s_waitcnt lgkmcnt(1)
	v_add_f32_e32 v56, v55, v56
	ds_bpermute_b32 v57, v85, v56
	s_waitcnt lgkmcnt(1)
	v_mul_f32_e32 v36, v16, v36
	v_mul_f32_e32 v37, v17, v37
	v_and_b32_e32 v95, 0xffff0000, v58
	v_cndmask_b32_e64 v37, v37, -v37, s[2:3]
	v_cndmask_b32_e64 v36, v36, -v36, s[2:3]
	s_waitcnt lgkmcnt(0)
	v_add_f32_e32 v56, v56, v57
	v_fmamk_f32 v56, v56, 0x3c000000, v87
	v_mul_f32_e32 v57, 0x4f800000, v56
	v_cmp_gt_f32_e32 vcc, s34, v56
	v_fma_f32 v34, v20, v34, v36
	v_fma_f32 v35, v21, v35, v37
	v_cndmask_b32_e32 v56, v56, v57, vcc
	v_sqrt_f32_e32 v57, v56
	v_pk_mul_f32 v[36:37], v[34:35], s[22:23] op_sel_hi:[1,0]
	v_pk_mul_f32 v[34:35], v[54:55], v[80:81] op_sel_hi:[0,1]
	v_mul_f32_e32 v34, v14, v34
	v_mul_f32_e32 v35, v15, v35
	v_add_u32_e32 v64, -1, v57
	v_fma_f32 v65, -v64, v57, v56
	v_cmp_ge_f32_e64 s[0:1], 0, v65
	v_add_u32_e32 v65, 1, v57
	ds_bpermute_b32 v54, v84, v34
	v_cndmask_b32_e64 v64, v57, v64, s[0:1]
	v_fma_f32 v57, -v65, v57, v56
	v_cmp_lt_f32_e64 s[0:1], 0, v57
	ds_bpermute_b32 v55, v84, v35
	v_cvt_pk_bf16_f32 v36, v36, v37
	v_cndmask_b32_e64 v57, v64, v65, s[0:1]
	v_mul_f32_e32 v64, 0x37800000, v57
	v_cndmask_b32_e32 v57, v57, v64, vcc
	v_cmp_class_f32_e32 vcc, v56, v88
	s_waitcnt lgkmcnt(0)
; __device__ __forceinline__ unsigned cvtpk(float lo, float hi) { const f32x2 v = {lo, hi}; const hbf16x2_t b = __builtin_convertvector(v, hbf16x2_t); return __builtin_bit_cast(unsigned, b); }
; template <int PH>
; __device__ __forceinline__ void run_phase(const Args& args, LAS unsigned char* lds) {
;     ...
;                     for (int h = 0; h < 10; ++h) {
;                         float x[8] = {bflo(raw[h].x), bfhi(raw[h].x), bflo(raw[h].y), bfhi(raw[h].y), bflo(raw[h].z), bfhi(raw[h].z), bflo(raw[h].w), bfhi(raw[h].w)};
;                         float ss = 0.f;
; #pragma unroll
;                         for (int k = 0; k < 8; ++k) ss += x[k] * x[k];
;                         ss += __shfl_xor(ss, 1); ss += __shfl_xor(ss, 2); ss += __shfl_xor(ss, 4); ss += __shfl_xor(ss, 8);
;                         const float rs = 1.0f / sqrtf(ss * (1.0f / 128.0f) + NEPS);
;                         float o[8];
; #pragma unroll
;                         for (int k = 0; k < 8; ++k) { const float y = x[k] * rs * (h < 8 ? qgv[k] : kgv[k]); const float yo = __shfl_xor(y, 4);
;                             o[k] = first ? (y * cs[k] - yo * sn[k]) : (yo * sn[k] + y * cs[k]); if (h < 8) o[k] *= QS; }
;                         u32x4 w; w.x = cvtpk(o[0], o[1]); w.y = cvtpk(o[2], o[3]); w.z = cvtpk(o[4], o[5]); w.w = cvtpk(o[6], o[7]);
;                         if (h < 8) *(u32x4*)(Qb + (size_t)row * 1024 + h * 128 + 8 * l16) = w;
;                         else *(u32x4*)(Kb + (size_t)(b * TK + Tpos) * 256 + (h - 8) * 128 + 8 * l16) = w;
	v_mul_f32_e32 v54, v18, v54
	v_mul_f32_e32 v55, v19, v55
	v_lshlrev_b32_e32 v80, 16, v59
	v_cndmask_b32_e32 v56, v57, v56, vcc
	v_div_scale_f32 v57, s[0:1], v56, v56, 1.0
	v_rcp_f32_e32 v64, v57
	v_cndmask_b32_e64 v55, v55, -v55, s[2:3]
	v_cndmask_b32_e64 v54, v54, -v54, s[2:3]
	v_fma_f32 v34, v72, v34, v54
	v_fma_f32 v35, v73, v35, v55
	v_and_b32_e32 v81, 0xffff0000, v59
	v_pk_mul_f32 v[54:55], v[34:35], s[22:23] op_sel_hi:[1,0]
	v_fma_f32 v35, -v57, v64, 1.0
	v_fmac_f32_e32 v64, v35, v64
	v_div_scale_f32 v35, vcc, 1.0, v56, 1.0
	v_cvt_pk_bf16_f32 v34, v42, v43
	v_mul_f32_e32 v42, v35, v64
	v_fma_f32 v43, -v57, v42, v35
	v_fmac_f32_e32 v42, v43, v64
	v_fma_f32 v35, -v57, v42, v35
	v_div_fmas_f32 v35, v35, v64, v42
	v_div_fixup_f32 v42, v35, v56, 1.0
	v_pk_mul_f32 v[56:57], v[42:43], v[98:99] op_sel_hi:[0,1]
	v_mul_f32_e32 v56, v4, v56
	v_mul_f32_e32 v57, v5, v57
	ds_bpermute_b32 v64, v84, v56
	ds_bpermute_b32 v65, v84, v57
	v_cvt_pk_bf16_f32 v35, v44, v45
	v_cvt_pk_bf16_f32 v37, v54, v55
	v_mul_f32_e32 v58, v94, v94
	v_mul_f32_e32 v59, v95, v95
	global_store_dwordx4 v[76:77], v[34:37], off offset:1280
	v_lshlrev_b32_e32 v54, 16, v61
	v_and_b32_e32 v55, 0xffff0000, v61
	v_pk_mul_f32 v[36:37], v[42:43], v[92:93] op_sel_hi:[0,1]
	v_mul_f32_e32 v92, v80, v80
	v_mul_f32_e32 v93, v81, v81
	v_add_f32_e32 v43, v58, v59
	s_waitcnt lgkmcnt(0)
	v_mul_f32_e32 v34, v26, v64
	v_mul_f32_e32 v35, v27, v65
	v_lshlrev_b32_e32 v64, 16, v60
	v_and_b32_e32 v65, 0xffff0000, v60
	v_add_f32_e32 v43, v92, v43
	v_mul_f32_e32 v60, v64, v64
	v_mul_f32_e32 v61, v65, v65
	v_add_f32_e32 v43, v93, v43
	v_cndmask_b32_e64 v35, v35, -v35, s[2:3]
	v_cndmask_b32_e64 v34, v34, -v34, s[2:3]
	v_add_f32_e32 v43, v60, v43
	v_fma_f32 v34, v28, v56, v34
	v_fma_f32 v35, v29, v57, v35
	v_mul_f32_e32 v56, v54, v54
	v_mul_f32_e32 v57, v55, v55
	v_add_f32_e32 v43, v61, v43
	v_add_f32_e32 v43, v56, v43
	v_add_f32_e32 v43, v57, v43
	ds_bpermute_b32 v60, v82, v43
	v_mul_f32_e32 v36, v6, v36
	v_mul_f32_e32 v37, v7, v37
	ds_bpermute_b32 v44, v84, v36
	ds_bpermute_b32 v45, v84, v37
	v_pk_mul_f32 v[56:57], v[42:43], v[90:91] op_sel_hi:[0,1]
	s_waitcnt lgkmcnt(2)
	v_add_f32_e32 v43, v43, v60
	v_mul_f32_e32 v56, v12, v56
	v_mul_f32_e32 v57, v13, v57
	ds_bpermute_b32 v60, v83, v43
	ds_bpermute_b32 v58, v84, v56
	ds_bpermute_b32 v59, v84, v57
	s_waitcnt lgkmcnt(3)
	v_mul_f32_e32 v44, v22, v44
	v_mul_f32_e32 v45, v23, v45
	v_pk_mul_f32 v[34:35], v[34:35], s[22:23] op_sel_hi:[1,0]
	v_cndmask_b32_e64 v45, v45, -v45, s[2:3]
	v_cndmask_b32_e64 v44, v44, -v44, s[2:3]
	s_waitcnt lgkmcnt(2)
	v_add_f32_e32 v43, v43, v60
	v_fma_f32 v36, v24, v36, v44
	v_fma_f32 v37, v25, v37, v45
	s_waitcnt lgkmcnt(0)
	v_mul_f32_e32 v44, v16, v58
	v_mul_f32_e32 v45, v17, v59
	ds_bpermute_b32 v58, v84, v43
	v_cndmask_b32_e64 v45, v45, -v45, s[2:3]
	v_cndmask_b32_e64 v44, v44, -v44, s[2:3]
	v_fma_f32 v44, v20, v56, v44
	v_fma_f32 v45, v21, v57, v45
	v_cvt_pk_bf16_f32 v34, v34, v35
	s_waitcnt lgkmcnt(0)
	v_add_f32_e32 v58, v43, v58
	ds_bpermute_b32 v59, v85, v58
	v_pk_mul_f32 v[42:43], v[42:43], v[62:63] op_sel_hi:[0,1]
	v_mul_f32_e32 v42, v14, v42
	v_mul_f32_e32 v43, v15, v43
	ds_bpermute_b32 v56, v84, v42
	ds_bpermute_b32 v57, v84, v43
	s_waitcnt lgkmcnt(2)
	v_add_f32_e32 v58, v58, v59
	v_fmamk_f32 v58, v58, 0x3c000000, v87
	v_mul_f32_e32 v59, 0x4f800000, v58
	v_cmp_gt_f32_e32 vcc, s34, v58
	s_waitcnt lgkmcnt(0)
	v_mul_f32_e32 v56, v18, v56
	v_mul_f32_e32 v57, v19, v57
	v_pk_mul_f32 v[36:37], v[36:37], s[22:23] op_sel_hi:[1,0]
	v_cndmask_b32_e32 v58, v58, v59, vcc
	v_sqrt_f32_e32 v59, v58
	v_cndmask_b32_e64 v57, v57, -v57, s[2:3]
	v_cndmask_b32_e64 v56, v56, -v56, s[2:3]
	v_fma_f32 v42, v72, v42, v56
	v_fma_f32 v43, v73, v43, v57
	v_add_u32_e32 v60, -1, v59
	v_fma_f32 v61, -v60, v59, v58
	v_cmp_ge_f32_e64 s[0:1], 0, v61
	v_add_u32_e32 v61, 1, v59
	v_pk_mul_f32 v[44:45], v[44:45], s[22:23] op_sel_hi:[1,0]
	v_cndmask_b32_e64 v60, v59, v60, s[0:1]
	v_fma_f32 v59, -v61, v59, v58
	v_cmp_lt_f32_e64 s[0:1], 0, v59
	v_pk_mul_f32 v[42:43], v[42:43], s[22:23] op_sel_hi:[1,0]
	s_waitcnt vmcnt(8)
	v_lshlrev_b32_e32 v92, 16, v46
	v_cndmask_b32_e64 v59, v60, v61, s[0:1]
	v_mul_f32_e32 v60, 0x37800000, v59
	v_cndmask_b32_e32 v59, v59, v60, vcc
	v_cmp_class_f32_e32 vcc, v58, v88
	v_and_b32_e32 v93, 0xffff0000, v46
	s_nop 0
	v_cndmask_b32_e32 v58, v59, v58, vcc
	v_div_scale_f32 v59, s[0:1], v58, v58, 1.0
	v_rcp_f32_e32 v60, v59
	s_nop 0
	v_fma_f32 v35, -v59, v60, 1.0
	v_fmac_f32_e32 v60, v35, v60
	v_div_scale_f32 v35, vcc, 1.0, v58, 1.0
	v_mul_f32_e32 v56, v35, v60
	v_fma_f32 v57, -v59, v56, v35
	v_fmac_f32_e32 v56, v57, v60
	v_fma_f32 v35, -v59, v56, v35
	v_div_fmas_f32 v35, v35, v60, v56
	v_div_fixup_f32 v56, v35, v58, 1.0
	v_pk_mul_f32 v[58:59], v[56:57], v[94:95] op_sel_hi:[0,1]
	v_mul_f32_e32 v58, v4, v58
	v_mul_f32_e32 v59, v5, v59
	ds_bpermute_b32 v60, v84, v58
	ds_bpermute_b32 v61, v84, v59
	v_cvt_pk_bf16_f32 v35, v36, v37
	v_cvt_pk_bf16_f32 v36, v44, v45
	v_cvt_pk_bf16_f32 v37, v42, v43
	global_store_dwordx4 v[76:77], v[34:37], off offset:1536
	v_pk_mul_f32 v[44:45], v[56:57], v[64:65] op_sel_hi:[0,1]
	v_lshlrev_b32_e32 v64, 16, v48
	v_pk_mul_f32 v[36:37], v[56:57], v[80:81] op_sel_hi:[0,1]
	v_lshlrev_b32_e32 v80, 16, v47
	v_and_b32_e32 v81, 0xffff0000, v47
	v_mul_f32_e32 v46, v92, v92
	v_mul_f32_e32 v47, v93, v93
	v_mul_f32_e32 v90, v80, v80
	v_mul_f32_e32 v91, v81, v81
	v_add_f32_e32 v46, v46, v47
	v_and_b32_e32 v65, 0xffff0000, v48
	v_add_f32_e32 v46, v90, v46
	s_waitcnt lgkmcnt(0)
; __device__ __forceinline__ unsigned cvtpk(float lo, float hi) { const f32x2 v = {lo, hi}; const hbf16x2_t b = __builtin_convertvector(v, hbf16x2_t); return __builtin_bit_cast(unsigned, b); }
; template <int PH>
; __device__ __forceinline__ void run_phase(const Args& args, LAS unsigned char* lds) {
;     ...
;                     for (int h = 0; h < 10; ++h) {
;                         float x[8] = {bflo(raw[h].x), bfhi(raw[h].x), bflo(raw[h].y), bfhi(raw[h].y), bflo(raw[h].z), bfhi(raw[h].z), bflo(raw[h].w), bfhi(raw[h].w)};
;                         float ss = 0.f;
; #pragma unroll
;                         for (int k = 0; k < 8; ++k) ss += x[k] * x[k];
;                         ss += __shfl_xor(ss, 1); ss += __shfl_xor(ss, 2); ss += __shfl_xor(ss, 4); ss += __shfl_xor(ss, 8);
;                         const float rs = 1.0f / sqrtf(ss * (1.0f / 128.0f) + NEPS);
;                         float o[8];
; #pragma unroll
;                         for (int k = 0; k < 8; ++k) { const float y = x[k] * rs * (h < 8 ? qgv[k] : kgv[k]); const float yo = __shfl_xor(y, 4);
;                             o[k] = first ? (y * cs[k] - yo * sn[k]) : (yo * sn[k] + y * cs[k]); if (h < 8) o[k] *= QS; }
;                         u32x4 w; w.x = cvtpk(o[0], o[1]); w.y = cvtpk(o[2], o[3]); w.z = cvtpk(o[4], o[5]); w.w = cvtpk(o[6], o[7]);
;                         if (h < 8) *(u32x4*)(Qb + (size_t)row * 1024 + h * 128 + 8 * l16) = w;
;                         else *(u32x4*)(Kb + (size_t)(b * TK + Tpos) * 256 + (h - 8) * 128 + 8 * l16) = w;
	v_mul_f32_e32 v34, v26, v60
	v_mul_f32_e32 v35, v27, v61
	v_lshlrev_b32_e32 v60, 16, v49
	v_and_b32_e32 v61, 0xffff0000, v49
	v_mul_f32_e32 v48, v64, v64
	v_mul_f32_e32 v49, v65, v65
	v_add_f32_e32 v46, v91, v46
	v_add_f32_e32 v46, v48, v46
	v_mul_f32_e32 v62, v60, v60
	v_mul_f32_e32 v63, v61, v61
	v_add_f32_e32 v46, v49, v46
	v_add_f32_e32 v46, v62, v46
	v_add_f32_e32 v46, v63, v46
	ds_bpermute_b32 v47, v82, v46
	v_mul_f32_e32 v36, v6, v36
	v_mul_f32_e32 v37, v7, v37
	ds_bpermute_b32 v42, v84, v36
	ds_bpermute_b32 v43, v84, v37
	v_cndmask_b32_e64 v35, v35, -v35, s[2:3]
	s_waitcnt lgkmcnt(2)
	v_add_f32_e32 v48, v46, v47
	ds_bpermute_b32 v49, v83, v48
	v_pk_mul_f32 v[46:47], v[56:57], v[54:55] op_sel_hi:[0,1]
	v_cndmask_b32_e64 v34, v34, -v34, s[2:3]
	v_mul_f32_e32 v44, v12, v44
	v_mul_f32_e32 v45, v13, v45
	v_fma_f32 v34, v28, v58, v34
	v_fma_f32 v35, v29, v59, v35
	s_waitcnt lgkmcnt(0)
	v_add_f32_e32 v54, v48, v49
	ds_bpermute_b32 v55, v84, v54
	ds_bpermute_b32 v58, v84, v44
	ds_bpermute_b32 v59, v84, v45
	v_mul_f32_e32 v46, v14, v46
	v_mul_f32_e32 v47, v15, v47
	ds_bpermute_b32 v48, v84, v46
	ds_bpermute_b32 v49, v84, v47
	v_mul_f32_e32 v42, v22, v42
	v_mul_f32_e32 v43, v23, v43
	s_waitcnt lgkmcnt(4)
	v_add_f32_e32 v54, v54, v55
	v_cndmask_b32_e64 v43, v43, -v43, s[2:3]
	v_cndmask_b32_e64 v42, v42, -v42, s[2:3]
	ds_bpermute_b32 v55, v85, v54
	v_fma_f32 v36, v24, v36, v42
	v_fma_f32 v37, v25, v37, v43
	s_waitcnt lgkmcnt(3)
	v_mul_f32_e32 v42, v16, v58
	v_mul_f32_e32 v43, v17, v59
	v_pk_mul_f32 v[34:35], v[34:35], s[22:23] op_sel_hi:[1,0]
	v_cndmask_b32_e64 v43, v43, -v43, s[2:3]
	v_cndmask_b32_e64 v42, v42, -v42, s[2:3]
	v_fma_f32 v42, v20, v44, v42
	v_fma_f32 v43, v21, v45, v43
	s_waitcnt lgkmcnt(1)
	v_mul_f32_e32 v44, v18, v48
	v_mul_f32_e32 v45, v19, v49
	v_pk_mul_f32 v[36:37], v[36:37], s[22:23] op_sel_hi:[1,0]
	v_cndmask_b32_e64 v45, v45, -v45, s[2:3]
	v_cndmask_b32_e64 v44, v44, -v44, s[2:3]
	v_fma_f32 v44, v72, v46, v44
	v_fma_f32 v45, v73, v47, v45
	s_waitcnt lgkmcnt(0)
	v_add_f32_e32 v46, v54, v55
	v_fmamk_f32 v46, v46, 0x3c000000, v87
	v_mul_f32_e32 v47, 0x4f800000, v46
	v_cmp_gt_f32_e32 vcc, s34, v46
	v_cvt_pk_bf16_f32 v34, v34, v35
	v_cvt_pk_bf16_f32 v35, v36, v37
	v_cndmask_b32_e32 v46, v46, v47, vcc
	v_sqrt_f32_e32 v47, v46
	v_pk_mul_f32 v[42:43], v[42:43], s[22:23] op_sel_hi:[1,0]
	v_pk_mul_f32 v[44:45], v[44:45], s[22:23] op_sel_hi:[1,0]
	s_waitcnt vmcnt(7)
	v_lshlrev_b32_e32 v62, 16, v51
	v_add_u32_e32 v36, -1, v47
	v_fma_f32 v37, -v36, v47, v46
	v_cmp_ge_f32_e64 s[0:1], 0, v37
	v_add_u32_e32 v37, 1, v47
	v_and_b32_e32 v63, 0xffff0000, v51
	v_cndmask_b32_e64 v36, v47, v36, s[0:1]
	v_fma_f32 v47, -v37, v47, v46
	v_cmp_lt_f32_e64 s[0:1], 0, v47
	v_lshlrev_b32_e32 v58, 16, v52
	v_and_b32_e32 v59, 0xffff0000, v52
	v_cndmask_b32_e64 v36, v36, v37, s[0:1]
	v_mul_f32_e32 v37, 0x37800000, v36
	v_cndmask_b32_e32 v36, v36, v37, vcc
	v_cmp_class_f32_e32 vcc, v46, v88
	v_cvt_pk_bf16_f32 v37, v44, v45
	v_lshlrev_b32_e32 v54, 16, v53
	v_cndmask_b32_e32 v46, v36, v46, vcc
	v_div_scale_f32 v47, s[0:1], v46, v46, 1.0
	v_rcp_f32_e32 v48, v47
	v_cvt_pk_bf16_f32 v36, v42, v43
	global_store_dwordx4 v[76:77], v[34:37], off offset:1792
	v_lshlrev_b32_e32 v76, 16, v50
	v_and_b32_e32 v77, 0xffff0000, v50
	v_fma_f32 v34, -v47, v48, 1.0
	v_fmac_f32_e32 v48, v34, v48
	v_div_scale_f32 v34, vcc, 1.0, v46, 1.0
	v_mul_f32_e32 v35, v34, v48
	v_fma_f32 v36, -v47, v35, v34
	v_fmac_f32_e32 v35, v36, v48
	v_fma_f32 v34, -v47, v35, v34
	v_div_fmas_f32 v34, v34, v48, v35
	v_div_fixup_f32 v34, v34, v46, 1.0
	v_pk_mul_f32 v[36:37], v[34:35], v[92:93] op_sel_hi:[0,1]
	v_mul_f32_e32 v36, v0, v36
	v_mul_f32_e32 v37, v1, v37
	ds_bpermute_b32 v42, v84, v36
	ds_bpermute_b32 v43, v84, v37
	v_pk_mul_f32 v[44:45], v[34:35], v[80:81] op_sel_hi:[0,1]
	v_mul_f32_e32 v44, v2, v44
	v_mul_f32_e32 v45, v3, v45
	ds_bpermute_b32 v46, v84, v44
	ds_bpermute_b32 v47, v84, v45
	s_waitcnt lgkmcnt(2)
	v_mul_f32_e32 v42, v26, v42
	v_mul_f32_e32 v43, v27, v43
	v_mul_f32_e32 v50, v76, v76
	v_mul_f32_e32 v51, v77, v77
	v_cndmask_b32_e64 v43, v43, -v43, s[2:3]
	v_cndmask_b32_e64 v42, v42, -v42, s[2:3]
	v_fma_f32 v36, v28, v36, v42
	v_fma_f32 v37, v29, v37, v43
	s_waitcnt lgkmcnt(0)
	v_mul_f32_e32 v42, v22, v46
	v_mul_f32_e32 v43, v23, v47
	v_pk_mul_f32 v[46:47], v[34:35], v[64:65] op_sel_hi:[0,1]
	v_mul_f32_e32 v64, v62, v62
	v_mul_f32_e32 v65, v63, v63
	v_add_f32_e32 v35, v50, v51
	v_add_f32_e32 v35, v64, v35
	v_and_b32_e32 v55, 0xffff0000, v53
	v_mul_f32_e32 v52, v58, v58
	v_mul_f32_e32 v53, v59, v59
	v_add_f32_e32 v35, v65, v35
	v_add_f32_e32 v35, v52, v35
	v_mul_f32_e32 v56, v54, v54
	v_mul_f32_e32 v57, v55, v55
	v_add_f32_e32 v35, v53, v35
	v_mul_f32_e32 v46, v8, v46
	v_mul_f32_e32 v47, v9, v47
	v_add_f32_e32 v35, v56, v35
	ds_bpermute_b32 v48, v84, v46
	ds_bpermute_b32 v49, v84, v47
	v_add_f32_e32 v50, v57, v35
	ds_bpermute_b32 v51, v82, v50
	v_cndmask_b32_e64 v43, v43, -v43, s[2:3]
	v_cndmask_b32_e64 v42, v42, -v42, s[2:3]
	v_fma_f32 v42, v24, v44, v42
	v_fma_f32 v43, v25, v45, v43
	s_waitcnt lgkmcnt(1)
	v_mul_f32_e32 v44, v16, v48
	v_mul_f32_e32 v45, v17, v49
	v_cndmask_b32_e64 v35, v45, -v45, s[2:3]
	s_waitcnt lgkmcnt(0)
; __device__ __forceinline__ unsigned cvtpk(float lo, float hi) { const f32x2 v = {lo, hi}; const hbf16x2_t b = __builtin_convertvector(v, hbf16x2_t); return __builtin_bit_cast(unsigned, b); }
; template <int PH>
; __device__ __forceinline__ void run_phase(const Args& args, LAS unsigned char* lds) {
;     ...
;                         for (int k = 0; k < 8; ++k) { const float y = x[k] * rs * (h < 8 ? qgv[k] : kgv[k]); const float yo = __shfl_xor(y, 4);
;                             o[k] = first ? (y * cs[k] - yo * sn[k]) : (yo * sn[k] + y * cs[k]); if (h < 8) o[k] *= QS; }
;                         u32x4 w; w.x = cvtpk(o[0], o[1]); w.y = cvtpk(o[2], o[3]); w.z = cvtpk(o[4], o[5]); w.w = cvtpk(o[6], o[7]);
;                         if (h < 8) *(u32x4*)(Qb + (size_t)row * 1024 + h * 128 + 8 * l16) = w;
;                         else *(u32x4*)(Kb + (size_t)(b * TK + Tpos) * 256 + (h - 8) * 128 + 8 * l16) = w;
;                     }
; #pragma unroll
;                     for (int h = 0; h < 2; ++h) { bf16_t* vp = VTb + (size_t)((b * 2 + h) * 128 + 8 * l16) * TK + Tpos; const u32x4 r = raw[10 + h];
;                         vp[0] = (bf16_t)(r.x & 0xffffu); vp[TK] = (bf16_t)(r.x >> 16); vp[2 * TK] = (bf16_t)(r.y & 0xffffu); vp[3 * TK] = (bf16_t)(r.y >> 16);
;                         vp[4 * TK] = (bf16_t)(r.z & 0xffffu); vp[5 * TK] = (bf16_t)(r.z >> 16); vp[6 * TK] = (bf16_t)(r.w & 0xffffu); vp[7 * TK] = (bf16_t)(r.w >> 16); }
	v_add_f32_e32 v45, v50, v51
	ds_bpermute_b32 v52, v83, v45
	v_pk_mul_f32 v[48:49], v[34:35], v[60:61] op_sel_hi:[0,1]
	v_mul_f32_e32 v48, v10, v48
	v_mul_f32_e32 v49, v11, v49
	ds_bpermute_b32 v50, v84, v48
	ds_bpermute_b32 v51, v84, v49
	s_waitcnt lgkmcnt(2)
	v_add_f32_e32 v52, v45, v52
	ds_bpermute_b32 v53, v84, v52
	v_cndmask_b32_e64 v34, v44, -v44, s[2:3]
	v_fma_f32 v44, v20, v46, v34
	v_fma_f32 v45, v21, v47, v35
	s_waitcnt lgkmcnt(1)
	v_mul_f32_e32 v34, v18, v50
	v_mul_f32_e32 v35, v19, v51
	s_waitcnt lgkmcnt(0)
	v_add_f32_e32 v50, v52, v53
	ds_bpermute_b32 v51, v85, v50
	v_cndmask_b32_e64 v35, v35, -v35, s[2:3]
	v_cndmask_b32_e64 v34, v34, -v34, s[2:3]
	v_fma_f32 v46, v72, v48, v34
	v_fma_f32 v47, v73, v49, v35
	v_cvt_pk_bf16_f32 v34, v36, v37
	s_waitcnt lgkmcnt(0)
	v_add_f32_e32 v36, v50, v51
	v_fmamk_f32 v36, v36, 0x3c000000, v87
	v_mul_f32_e32 v37, 0x4f800000, v36
	v_cmp_gt_f32_e32 vcc, s34, v36
	v_cvt_pk_bf16_f32 v35, v42, v43
	v_lshl_add_u64 v[42:43], v[78:79], 0, v[68:69]
	v_cndmask_b32_e32 v48, v36, v37, vcc
	v_sqrt_f32_e32 v49, v48
	v_cvt_pk_bf16_f32 v36, v44, v45
	v_cvt_pk_bf16_f32 v37, v46, v47
	v_lshlrev_b32_e32 v68, 1, v74
	v_add_u32_e32 v44, -1, v49
	v_fma_f32 v45, -v44, v49, v48
	v_cmp_ge_f32_e64 s[0:1], 0, v45
	v_add_u32_e32 v45, 1, v49
	v_fma_f32 v46, -v45, v49, v48
	v_cndmask_b32_e64 v44, v49, v44, s[0:1]
	v_cmp_lt_f32_e64 s[0:1], 0, v46
	s_nop 1
	v_cndmask_b32_e64 v44, v44, v45, s[0:1]
	v_mul_f32_e32 v45, 0x37800000, v44
	v_cndmask_b32_e32 v44, v44, v45, vcc
	v_cmp_class_f32_e32 vcc, v48, v88
	s_nop 1
	v_cndmask_b32_e32 v44, v44, v48, vcc
	v_div_scale_f32 v45, s[0:1], v44, v44, 1.0
	v_rcp_f32_e32 v46, v45
	v_add_co_u32_e32 v42, vcc, s35, v42
	s_nop 1
	v_addc_co_u32_e32 v43, vcc, 0, v43, vcc
	global_store_dwordx4 v[42:43], v[34:37], off
	s_nop 1
	v_fma_f32 v34, -v45, v46, 1.0
	v_fmac_f32_e32 v46, v34, v46
	v_div_scale_f32 v34, vcc, 1.0, v44, 1.0
	v_mul_f32_e32 v35, v34, v46
	v_fma_f32 v36, -v45, v35, v34
	v_fmac_f32_e32 v35, v36, v46
	v_fma_f32 v34, -v45, v35, v34
	v_div_fmas_f32 v34, v34, v46, v35
	v_div_fixup_f32 v34, v34, v44, 1.0
	v_pk_mul_f32 v[46:47], v[34:35], v[62:63] op_sel_hi:[0,1]
	v_mul_f32_e32 v46, v2, v46
	v_mul_f32_e32 v47, v3, v47
	v_pk_mul_f32 v[36:37], v[34:35], v[76:77] op_sel_hi:[0,1]
	ds_bpermute_b32 v48, v84, v46
	ds_bpermute_b32 v49, v84, v47
	v_mul_f32_e32 v36, v0, v36
	v_mul_f32_e32 v37, v1, v37
	ds_bpermute_b32 v44, v84, v36
	ds_bpermute_b32 v45, v84, v37
	s_waitcnt lgkmcnt(2)
	v_mul_f32_e32 v22, v22, v48
	v_mul_f32_e32 v23, v23, v49
	v_cndmask_b32_e64 v23, v23, -v23, s[2:3]
	v_cndmask_b32_e64 v22, v22, -v22, s[2:3]
	s_waitcnt lgkmcnt(0)
	v_mul_f32_e32 v26, v26, v44
	v_mul_f32_e32 v27, v27, v45
	v_fma_f32 v22, v24, v46, v22
	v_fma_f32 v23, v25, v47, v23
	v_pk_mul_f32 v[24:25], v[34:35], v[58:59] op_sel_hi:[0,1]
	v_cndmask_b32_e64 v27, v27, -v27, s[2:3]
	v_cndmask_b32_e64 v26, v26, -v26, s[2:3]
	v_mul_f32_e32 v24, v8, v24
	v_mul_f32_e32 v25, v9, v25
	v_fma_f32 v26, v28, v36, v26
	v_fma_f32 v27, v29, v37, v27
	ds_bpermute_b32 v28, v84, v24
	ds_bpermute_b32 v29, v84, v25
	v_pk_mul_f32 v[34:35], v[34:35], v[54:55] op_sel_hi:[0,1]
	v_mul_f32_e32 v34, v10, v34
	v_mul_f32_e32 v35, v11, v35
	ds_bpermute_b32 v36, v84, v34
	ds_bpermute_b32 v37, v84, v35
	s_waitcnt lgkmcnt(2)
	v_mul_f32_e32 v16, v16, v28
	v_mul_f32_e32 v17, v17, v29
	v_cndmask_b32_e64 v17, v17, -v17, s[2:3]
	v_cndmask_b32_e64 v16, v16, -v16, s[2:3]
	v_fma_f32 v20, v20, v24, v16
	v_fma_f32 v21, v21, v25, v17
	s_waitcnt lgkmcnt(0)
	v_mul_f32_e32 v16, v18, v36
	v_mul_f32_e32 v17, v19, v37
	v_cvt_pk_bf16_f32 v18, v20, v21
	v_cndmask_b32_e64 v17, v17, -v17, s[2:3]
	v_cndmask_b32_e64 v16, v16, -v16, s[2:3]
	v_fma_f32 v24, v72, v34, v16
	v_fma_f32 v25, v73, v35, v17
	v_cvt_pk_bf16_f32 v16, v26, v27
	v_cvt_pk_bf16_f32 v17, v22, v23
	v_cvt_pk_bf16_f32 v19, v24, v25
	global_store_dwordx4 v[42:43], v[16:19], off offset:256
	v_lshl_or_b32 v22, v89, 8, v66
	s_nop 0
	v_lshl_add_u64 v[16:17], s[8:9], 0, v[68:69]
	v_mad_i64_i32 v[18:19], s[0:1], v22, s36, v[16:17]
	v_add_co_u32_e32 v20, vcc, s30, v18
	s_waitcnt vmcnt(9)
	v_addc_co_u32_e32 v21, vcc, 0, v19, vcc
	v_add_co_u32_e32 v20, vcc, s37, v18
	s_nop 1
	v_addc_co_u32_e32 v21, vcc, 0, v19, vcc
	v_add_co_u32_e32 v20, vcc, s38, v18
	s_nop 1
	v_addc_co_u32_e32 v21, vcc, 0, v19, vcc
	v_add_co_u32_e32 v20, vcc, s28, v18
	s_nop 1
	v_addc_co_u32_e32 v21, vcc, 0, v19, vcc
	v_add_co_u32_e32 v20, vcc, s39, v18
	s_nop 1
	v_addc_co_u32_e32 v21, vcc, 0, v19, vcc
	v_add_co_u32_e32 v20, vcc, s44, v18
	s_nop 1
	v_addc_co_u32_e32 v21, vcc, 0, v19, vcc
	v_add_co_u32_e32 v18, vcc, s45, v18
	s_nop 0
	v_addc_co_u32_e32 v19, vcc, 0, v19, vcc
	v_or_b32_e32 v18, 0x80, v22
	v_mad_i64_i32 v[16:17], s[0:1], v18, s36, v[16:17]
	v_add_co_u32_e32 v18, vcc, s30, v16
	s_nop 0
	v_addc_co_u32_e32 v19, vcc, 0, v17, vcc
	v_add_co_u32_e32 v18, vcc, s37, v16
	s_nop 1
	v_addc_co_u32_e32 v19, vcc, 0, v17, vcc
	v_add_co_u32_e32 v18, vcc, s38, v16
	s_nop 1
	v_addc_co_u32_e32 v19, vcc, 0, v17, vcc
	v_add_co_u32_e32 v18, vcc, s28, v16
	s_nop 1
	v_addc_co_u32_e32 v19, vcc, 0, v17, vcc
	v_add_co_u32_e32 v18, vcc, s39, v16
	s_nop 1
	v_addc_co_u32_e32 v19, vcc, 0, v17, vcc
	v_add_co_u32_e32 v18, vcc, 0x6000, v16
	s_nop 1
	v_addc_co_u32_e32 v19, vcc, 0, v17, vcc
	v_add_co_u32_e32 v16, vcc, 0x7000, v16
	s_nop 0
	v_addc_co_u32_e32 v17, vcc, 0, v17, vcc
	s_cbranch_scc1 .LBB0_296
